# v45 plus padded rowss hoist in W_in and FFN2 epilogues, scan batch wait moved below the next loads, nt policy on once-read x loads (P2) and final output stores (P9)
# baseline (speedup 1.0000x reference)
; #define PG8_STAGE(bufoff, gbase, voff) do { _Pragma("unroll") for (int _i = 0; _i < 2; ++_i) \
;         __builtin_amdgcn_global_load_lds((const unsigned*)((const char*)(gbase) + (voff)[_i]), (PG8_LAS unsigned*)(lds + (bufoff) + ldsw + _i * 8192), 16, 0, 0); } while (0)
; #define PG8_LDA(dst, b, h) do { _Pragma("unroll") for (int m = 0; m < 4; ++m) _Pragma("unroll") for (int k = 0; k < 2; ++k) dst[m][k] = *(const PG8_LAS bf16x8*)(lds + PG8_SA(b, h) + aoff + m * 2048 + k * 1024); } while (0)
; #define PG8_LDB(dst, b, h) do { _Pragma("unroll") for (int n = 0; n < 2; ++n) _Pragma("unroll") for (int k = 0; k < 2; ++k) dst[n][k] = *(const PG8_LAS bf16x8*)(lds + PG8_SB(b, h) + boff + n * 2048 + k * 1024); } while (0)
; #define PG8_MMA(ai, bj, At, Bt) do { __builtin_amdgcn_s_setprio(1); _Pragma("unroll") for (int m = 0; m < 4; ++m) _Pragma("unroll") for (int n = 0; n < 2; ++n) _Pragma("unroll") for (int k = 0; k < 2; ++k) \
;         acc[ai][bj][m][n] = __builtin_amdgcn_mfma_f32_16x16x32_bf16(Bt[n][k], At[m][k], acc[ai][bj][m][n], 0, 0, 0); __builtin_amdgcn_s_setprio(0); } while (0)
; #define PG8_BAR __builtin_amdgcn_s_barrier()
; template <class Epi, class Sched, bool ALIGN_EPI = false, bool SP2 = false>
; __device__ __forceinline__ void gemm_phase(PG8_LAS unsigned char* lds, const Gemm g, const Sched& S, const Epi& E, int wave_in) {
;     ...
;             PG8_LDB(B0, 0, 0); PG8_LDB(B1, 0, 1); PG8_SCHED; PG8_LDA(At, 0, 0); PG8_STAGE(PG8_SA(1, 1), a1 + hstep, voffA);
;             PG8_WAIT_V(8); PG8_WAIT_L(0); PG8_BAR; PG8_MMA(0, 0, At, B0); PG8_MMA(0, 1, At, B1); PG8_BAR; PG8_SCHED;
;             PG8_LDA(At, 0, 1); PG8_STAGE(PG8_SB(0, 0), b2, voffB); PG8_STAGE(PG8_SB(0, 1), b2 + hstep, voffB); PG8_STAGE(PG8_SA(0, 0), a2, voffA);
;             PG8_WAIT_V(8); PG8_WAIT_L(0); PG8_BAR; PG8_MMA(1, 0, At, B0); PG8_MMA(1, 1, At, B1); PG8_BAR; PG8_SCHED;
;             PG8_LDB(B0, 1, 0); PG8_LDB(B1, 1, 1); PG8_SCHED; PG8_LDA(At, 1, 0); PG8_STAGE(PG8_SA(0, 1), a2 + hstep, voffA);
;             PG8_WAIT_V(8); PG8_WAIT_L(0); PG8_BAR; PG8_MMA(0, 0, At, B0); PG8_MMA(0, 1, At, B1); PG8_BAR; PG8_SCHED;
;             PG8_LDA(At, 1, 1); PG8_STAGE(PG8_SB(1, 0), b3, voffB); PG8_STAGE(PG8_SB(1, 1), b3 + hstep, voffB); PG8_STAGE(PG8_SA(1, 0), a3, voffA);
;             PG8_WAIT_V(8); PG8_WAIT_L(0); PG8_BAR; PG8_MMA(1, 0, At, B0); PG8_MMA(1, 1, At, B1); PG8_BAR; PG8_SCHED;
.LBB0_307:
	ds_read_b128 v[140:143], v147
	ds_read_b128 v[152:155], v147 offset:1024
	ds_read_b128 v[156:159], v147 offset:2048
	ds_read_b128 v[160:163], v147 offset:3072
	ds_read_b128 v[168:171], v148
	ds_read_b128 v[172:175], v148 offset:1024
	ds_read_b128 v[176:179], v148 offset:2048
	ds_read_b128 v[180:183], v148 offset:3072
	s_add_u32 s28, s26, 0x100
	s_addc_u32 s29, s27, 0
	s_cmpk_eq_i32 s55, 0x54
	s_cselect_b32 s35, s5, s29
	s_cselect_b32 s34, s4, s28
	s_cselect_b32 s31, s25, s54
	s_cselect_b32 s30, s24, s53
	v_lshl_add_u64 v[164:165], s[26:27], 0, v[132:133]
	s_add_i32 m0, s37, 0xc000
	ds_read_b128 v[184:187], v149
	ds_read_b128 v[188:191], v149 offset:1024
	ds_read_b128 v[192:195], v149 offset:2048
	ds_read_b128 v[196:199], v149 offset:3072
	ds_read_b128 v[200:203], v149 offset:4096
	ds_read_b128 v[204:207], v149 offset:5120
	ds_read_b128 v[208:211], v149 offset:6144
	ds_read_b128 v[212:215], v149 offset:7168
	global_load_lds_dwordx4 v[164:165], off
	v_lshl_add_u64 v[164:165], s[26:27], 0, v[134:135]
	s_add_i32 m0, s37, 0xe000
	s_nop 0
	global_load_lds_dwordx4 v[164:165], off
	s_waitcnt vmcnt(8)
	s_waitcnt lgkmcnt(0)
	s_barrier
	s_setprio 1
	s_waitcnt lgkmcnt(0)
	v_mfma_f32_16x16x32_bf16 v[124:127], v[140:143], v[184:187], v[124:127]
	v_mfma_f32_16x16x32_bf16 v[120:123], v[156:159], v[184:187], v[120:123]
	v_mfma_f32_16x16x32_bf16 v[108:111], v[140:143], v[192:195], v[108:111]
	v_mfma_f32_16x16x32_bf16 v[104:107], v[156:159], v[192:195], v[104:107]
	v_mfma_f32_16x16x32_bf16 v[92:95], v[140:143], v[200:203], v[92:95]
	v_mfma_f32_16x16x32_bf16 v[88:91], v[156:159], v[200:203], v[88:91]
	v_mfma_f32_16x16x32_bf16 v[76:79], v[140:143], v[208:211], v[76:79]
	v_mfma_f32_16x16x32_bf16 v[72:75], v[156:159], v[208:211], v[72:75]
	v_mfma_f32_16x16x32_bf16 v[124:127], v[152:155], v[188:191], v[124:127]
	v_mfma_f32_16x16x32_bf16 v[120:123], v[160:163], v[188:191], v[120:123]
	v_mfma_f32_16x16x32_bf16 v[108:111], v[152:155], v[196:199], v[108:111]
	v_mfma_f32_16x16x32_bf16 v[104:107], v[160:163], v[196:199], v[104:107]
	v_mfma_f32_16x16x32_bf16 v[92:95], v[152:155], v[204:207], v[92:95]
	v_mfma_f32_16x16x32_bf16 v[88:91], v[160:163], v[204:207], v[88:91]
	v_mfma_f32_16x16x32_bf16 v[76:79], v[152:155], v[212:215], v[76:79]
	v_mfma_f32_16x16x32_bf16 v[72:75], v[160:163], v[212:215], v[72:75]
	s_setprio 0
	s_setprio 1
	v_mfma_f32_16x16x32_bf16 v[116:119], v[168:171], v[184:187], v[116:119]
	v_mfma_f32_16x16x32_bf16 v[112:115], v[176:179], v[184:187], v[112:115]
	v_mfma_f32_16x16x32_bf16 v[100:103], v[168:171], v[192:195], v[100:103]
	v_mfma_f32_16x16x32_bf16 v[96:99], v[176:179], v[192:195], v[96:99]
	v_mfma_f32_16x16x32_bf16 v[84:87], v[168:171], v[200:203], v[84:87]
	v_mfma_f32_16x16x32_bf16 v[80:83], v[176:179], v[200:203], v[80:83]
	v_mfma_f32_16x16x32_bf16 v[68:71], v[168:171], v[208:211], v[68:71]
	v_mfma_f32_16x16x32_bf16 v[64:67], v[176:179], v[208:211], v[64:67]
	v_mfma_f32_16x16x32_bf16 v[116:119], v[172:175], v[188:191], v[116:119]
	v_mfma_f32_16x16x32_bf16 v[112:115], v[180:183], v[188:191], v[112:115]
	v_mfma_f32_16x16x32_bf16 v[100:103], v[172:175], v[196:199], v[100:103]
	v_mfma_f32_16x16x32_bf16 v[96:99], v[180:183], v[196:199], v[96:99]
	s_barrier
	s_setprio 3
	v_mfma_f32_16x16x32_bf16 v[84:87], v[172:175], v[204:207], v[84:87]
	v_mfma_f32_16x16x32_bf16 v[80:83], v[180:183], v[204:207], v[80:83]
	v_mfma_f32_16x16x32_bf16 v[68:71], v[172:175], v[212:215], v[68:71]
	v_mfma_f32_16x16x32_bf16 v[64:67], v[180:183], v[212:215], v[64:67]
	s_setprio 0
	s_add_i32 s26, s47, s21
	v_lshl_add_u64 v[164:165], s[30:31], 0, v[128:129]
	s_mov_b32 m0, s26
	ds_read_b128 v[184:187], v149 offset:16384
	ds_read_b128 v[188:191], v149 offset:17408
	ds_read_b128 v[192:195], v149 offset:18432
	ds_read_b128 v[196:199], v149 offset:19456
	ds_read_b128 v[200:203], v149 offset:20480
	ds_read_b128 v[204:207], v149 offset:21504
	ds_read_b128 v[208:211], v149 offset:22528
	ds_read_b128 v[212:215], v149 offset:23552
	global_load_lds_dwordx4 v[164:165], off
	s_add_i32 m0, s26, 0x2000
	s_add_u32 s26, s30, 0x160000
	v_lshl_add_u64 v[166:167], s[30:31], 0, v[130:131]
	s_addc_u32 s27, s31, 0
	s_add_i32 s56, s48, s21
	global_load_lds_dwordx4 v[166:167], off
	v_lshl_add_u64 v[216:217], s[26:27], 0, v[128:129]
	s_mov_b32 m0, s56
	v_lshl_add_u64 v[218:219], s[34:35], 0, v[130:131]
	global_load_lds_dwordx4 v[216:217], off
	v_lshl_add_u64 v[216:217], s[26:27], 0, v[130:131]
	s_add_i32 m0, s56, 0x2000
	s_nop 0
	global_load_lds_dwordx4 v[216:217], off
	v_lshl_add_u64 v[216:217], s[34:35], 0, v[128:129]
	s_mov_b32 m0, s37
	s_nop 0
	global_load_lds_dwordx4 v[216:217], off
	s_mov_b32 m0, s38
	s_nop 0
	global_load_lds_dwordx4 v[218:219], off
	s_waitcnt vmcnt(8)
	s_waitcnt lgkmcnt(0)
	s_barrier
; #define PG8_STAGE(bufoff, gbase, voff) do { _Pragma("unroll") for (int _i = 0; _i < 2; ++_i) \
;         __builtin_amdgcn_global_load_lds((const unsigned*)((const char*)(gbase) + (voff)[_i]), (PG8_LAS unsigned*)(lds + (bufoff) + ldsw + _i * 8192), 16, 0, 0); } while (0)
; #define PG8_LDA(dst, b, h) do { _Pragma("unroll") for (int m = 0; m < 4; ++m) _Pragma("unroll") for (int k = 0; k < 2; ++k) dst[m][k] = *(const PG8_LAS bf16x8*)(lds + PG8_SA(b, h) + aoff + m * 2048 + k * 1024); } while (0)
; #define PG8_LDB(dst, b, h) do { _Pragma("unroll") for (int n = 0; n < 2; ++n) _Pragma("unroll") for (int k = 0; k < 2; ++k) dst[n][k] = *(const PG8_LAS bf16x8*)(lds + PG8_SB(b, h) + boff + n * 2048 + k * 1024); } while (0)
; #define PG8_MMA(ai, bj, At, Bt) do { __builtin_amdgcn_s_setprio(1); _Pragma("unroll") for (int m = 0; m < 4; ++m) _Pragma("unroll") for (int n = 0; n < 2; ++n) _Pragma("unroll") for (int k = 0; k < 2; ++k) \
;         acc[ai][bj][m][n] = __builtin_amdgcn_mfma_f32_16x16x32_bf16(Bt[n][k], At[m][k], acc[ai][bj][m][n], 0, 0, 0); __builtin_amdgcn_s_setprio(0); } while (0)
; #define PG8_BAR __builtin_amdgcn_s_barrier()
; template <class Epi, class Sched, bool ALIGN_EPI = false, bool SP2 = false>
; __device__ __forceinline__ void gemm_phase(PG8_LAS unsigned char* lds, const Gemm g, const Sched& S, const Epi& E, int wave_in) {
;     ...
;             PG8_LDB(B0, 0, 0); PG8_LDB(B1, 0, 1); PG8_SCHED; PG8_LDA(At, 0, 0); PG8_STAGE(PG8_SA(1, 1), a1 + hstep, voffA);
;             PG8_WAIT_V(8); PG8_WAIT_L(0); PG8_BAR; PG8_MMA(0, 0, At, B0); PG8_MMA(0, 1, At, B1); PG8_BAR; PG8_SCHED;
;             PG8_LDA(At, 0, 1); PG8_STAGE(PG8_SB(0, 0), b2, voffB); PG8_STAGE(PG8_SB(0, 1), b2 + hstep, voffB); PG8_STAGE(PG8_SA(0, 0), a2, voffA);
;             PG8_WAIT_V(8); PG8_WAIT_L(0); PG8_BAR; PG8_MMA(1, 0, At, B0); PG8_MMA(1, 1, At, B1); PG8_BAR; PG8_SCHED;
;             PG8_LDB(B0, 1, 0); PG8_LDB(B1, 1, 1); PG8_SCHED; PG8_LDA(At, 1, 0); PG8_STAGE(PG8_SA(0, 1), a2 + hstep, voffA);
;             PG8_WAIT_V(8); PG8_WAIT_L(0); PG8_BAR; PG8_MMA(0, 0, At, B0); PG8_MMA(0, 1, At, B1); PG8_BAR; PG8_SCHED;
;             PG8_LDA(At, 1, 1); PG8_STAGE(PG8_SB(1, 0), b3, voffB); PG8_STAGE(PG8_SB(1, 1), b3 + hstep, voffB); PG8_STAGE(PG8_SA(1, 0), a3, voffA);
;             PG8_WAIT_V(8); PG8_WAIT_L(0); PG8_BAR; PG8_MMA(1, 0, At, B0); PG8_MMA(1, 1, At, B1); PG8_BAR; PG8_SCHED;
	s_setprio 1
	s_waitcnt lgkmcnt(0)
	v_mfma_f32_16x16x32_bf16 v[60:63], v[140:143], v[184:187], v[60:63]
	v_mfma_f32_16x16x32_bf16 v[56:59], v[156:159], v[184:187], v[56:59]
	v_mfma_f32_16x16x32_bf16 v[44:47], v[140:143], v[192:195], v[44:47]
	v_mfma_f32_16x16x32_bf16 v[40:43], v[156:159], v[192:195], v[40:43]
	v_mfma_f32_16x16x32_bf16 v[28:31], v[140:143], v[200:203], v[28:31]
	v_mfma_f32_16x16x32_bf16 v[24:27], v[156:159], v[200:203], v[24:27]
	v_mfma_f32_16x16x32_bf16 v[12:15], v[140:143], v[208:211], v[12:15]
	v_mfma_f32_16x16x32_bf16 v[8:11], v[156:159], v[208:211], v[8:11]
	v_mfma_f32_16x16x32_bf16 v[60:63], v[152:155], v[188:191], v[60:63]
	v_mfma_f32_16x16x32_bf16 v[56:59], v[160:163], v[188:191], v[56:59]
	v_mfma_f32_16x16x32_bf16 v[44:47], v[152:155], v[196:199], v[44:47]
	v_mfma_f32_16x16x32_bf16 v[40:43], v[160:163], v[196:199], v[40:43]
	v_mfma_f32_16x16x32_bf16 v[28:31], v[152:155], v[204:207], v[28:31]
	v_mfma_f32_16x16x32_bf16 v[24:27], v[160:163], v[204:207], v[24:27]
	v_mfma_f32_16x16x32_bf16 v[12:15], v[152:155], v[212:215], v[12:15]
	v_mfma_f32_16x16x32_bf16 v[8:11], v[160:163], v[212:215], v[8:11]
	s_setprio 0
	s_setprio 1
	v_mfma_f32_16x16x32_bf16 v[52:55], v[168:171], v[184:187], v[52:55]
	v_mfma_f32_16x16x32_bf16 v[48:51], v[176:179], v[184:187], v[48:51]
	v_mfma_f32_16x16x32_bf16 v[36:39], v[168:171], v[192:195], v[36:39]
	v_mfma_f32_16x16x32_bf16 v[32:35], v[176:179], v[192:195], v[32:35]
	v_mfma_f32_16x16x32_bf16 v[20:23], v[168:171], v[200:203], v[20:23]
	v_mfma_f32_16x16x32_bf16 v[16:19], v[176:179], v[200:203], v[16:19]
	v_mfma_f32_16x16x32_bf16 v[4:7], v[168:171], v[208:211], v[4:7]
	v_mfma_f32_16x16x32_bf16 v[0:3], v[176:179], v[208:211], v[0:3]
	v_mfma_f32_16x16x32_bf16 v[52:55], v[172:175], v[188:191], v[52:55]
	v_mfma_f32_16x16x32_bf16 v[48:51], v[180:183], v[188:191], v[48:51]
	v_mfma_f32_16x16x32_bf16 v[36:39], v[172:175], v[196:199], v[36:39]
	v_mfma_f32_16x16x32_bf16 v[32:35], v[180:183], v[196:199], v[32:35]
	s_barrier
	s_setprio 3
	v_mfma_f32_16x16x32_bf16 v[20:23], v[172:175], v[204:207], v[20:23]
	v_mfma_f32_16x16x32_bf16 v[16:19], v[180:183], v[204:207], v[16:19]
	v_mfma_f32_16x16x32_bf16 v[4:7], v[172:175], v[212:215], v[4:7]
	v_mfma_f32_16x16x32_bf16 v[0:3], v[180:183], v[212:215], v[0:3]
	s_setprio 0
	s_add_i32 s56, 0, 0x18000
	v_add_u32_e32 v151, s56, v145
	s_add_i32 s57, 0, 0x1c000
	ds_read_b128 v[140:143], v151
	ds_read_b128 v[152:155], v151 offset:1024
	ds_read_b128 v[156:159], v151 offset:2048
	ds_read_b128 v[160:163], v151 offset:3072
	v_add_u32_e32 v151, s57, v145
	ds_read_b128 v[168:171], v151
	ds_read_b128 v[172:175], v151 offset:1024
	ds_read_b128 v[176:179], v151 offset:2048
	ds_read_b128 v[180:183], v151 offset:3072
	s_add_u32 s26, s34, 0x160000
	s_addc_u32 s27, s35, 0
	s_mov_b32 m0, s39
	v_lshl_add_u64 v[220:221], s[26:27], 0, v[128:129]
	ds_read_b128 v[184:187], v149 offset:32768
	ds_read_b128 v[188:191], v149 offset:33792
	ds_read_b128 v[192:195], v149 offset:34816
	ds_read_b128 v[196:199], v149 offset:35840
	ds_read_b128 v[200:203], v149 offset:36864
	ds_read_b128 v[204:207], v149 offset:37888
	ds_read_b128 v[208:211], v149 offset:38912
	ds_read_b128 v[212:215], v149 offset:39936
	global_load_lds_dwordx4 v[220:221], off
	v_lshl_add_u64 v[220:221], s[26:27], 0, v[130:131]
	s_mov_b32 m0, s40
	s_nop 0
	global_load_lds_dwordx4 v[220:221], off
	s_waitcnt vmcnt(8)
	s_waitcnt lgkmcnt(0)
	s_barrier
	s_setprio 1
	s_waitcnt lgkmcnt(0)
	v_mfma_f32_16x16x32_bf16 v[124:127], v[140:143], v[184:187], v[124:127]
	v_mfma_f32_16x16x32_bf16 v[120:123], v[156:159], v[184:187], v[120:123]
	v_mfma_f32_16x16x32_bf16 v[108:111], v[140:143], v[192:195], v[108:111]
	v_mfma_f32_16x16x32_bf16 v[104:107], v[156:159], v[192:195], v[104:107]
	v_mfma_f32_16x16x32_bf16 v[92:95], v[140:143], v[200:203], v[92:95]
	v_mfma_f32_16x16x32_bf16 v[88:91], v[156:159], v[200:203], v[88:91]
	v_mfma_f32_16x16x32_bf16 v[76:79], v[140:143], v[208:211], v[76:79]
	v_mfma_f32_16x16x32_bf16 v[72:75], v[156:159], v[208:211], v[72:75]
	v_mfma_f32_16x16x32_bf16 v[124:127], v[152:155], v[188:191], v[124:127]
	v_mfma_f32_16x16x32_bf16 v[120:123], v[160:163], v[188:191], v[120:123]
	v_mfma_f32_16x16x32_bf16 v[108:111], v[152:155], v[196:199], v[108:111]
	v_mfma_f32_16x16x32_bf16 v[104:107], v[160:163], v[196:199], v[104:107]
	v_mfma_f32_16x16x32_bf16 v[92:95], v[152:155], v[204:207], v[92:95]
	v_mfma_f32_16x16x32_bf16 v[88:91], v[160:163], v[204:207], v[88:91]
	v_mfma_f32_16x16x32_bf16 v[76:79], v[152:155], v[212:215], v[76:79]
	v_mfma_f32_16x16x32_bf16 v[72:75], v[160:163], v[212:215], v[72:75]
	s_setprio 0
	s_setprio 1
	v_mfma_f32_16x16x32_bf16 v[116:119], v[168:171], v[184:187], v[116:119]
	v_mfma_f32_16x16x32_bf16 v[112:115], v[176:179], v[184:187], v[112:115]
	v_mfma_f32_16x16x32_bf16 v[100:103], v[168:171], v[192:195], v[100:103]
	v_mfma_f32_16x16x32_bf16 v[96:99], v[176:179], v[192:195], v[96:99]
	v_mfma_f32_16x16x32_bf16 v[84:87], v[168:171], v[200:203], v[84:87]
	v_mfma_f32_16x16x32_bf16 v[80:83], v[176:179], v[200:203], v[80:83]
	v_mfma_f32_16x16x32_bf16 v[68:71], v[168:171], v[208:211], v[68:71]
	v_mfma_f32_16x16x32_bf16 v[64:67], v[176:179], v[208:211], v[64:67]
	v_mfma_f32_16x16x32_bf16 v[116:119], v[172:175], v[188:191], v[116:119]
	v_mfma_f32_16x16x32_bf16 v[112:115], v[180:183], v[188:191], v[112:115]
	v_mfma_f32_16x16x32_bf16 v[100:103], v[172:175], v[196:199], v[100:103]
	v_mfma_f32_16x16x32_bf16 v[96:99], v[180:183], v[196:199], v[96:99]
	s_barrier
; #define PG8_STAGE(bufoff, gbase, voff) do { _Pragma("unroll") for (int _i = 0; _i < 2; ++_i) \
;         __builtin_amdgcn_global_load_lds((const unsigned*)((const char*)(gbase) + (voff)[_i]), (PG8_LAS unsigned*)(lds + (bufoff) + ldsw + _i * 8192), 16, 0, 0); } while (0)
; #define PG8_LDA(dst, b, h) do { _Pragma("unroll") for (int m = 0; m < 4; ++m) _Pragma("unroll") for (int k = 0; k < 2; ++k) dst[m][k] = *(const PG8_LAS bf16x8*)(lds + PG8_SA(b, h) + aoff + m * 2048 + k * 1024); } while (0)
; #define PG8_LDB(dst, b, h) do { _Pragma("unroll") for (int n = 0; n < 2; ++n) _Pragma("unroll") for (int k = 0; k < 2; ++k) dst[n][k] = *(const PG8_LAS bf16x8*)(lds + PG8_SB(b, h) + boff + n * 2048 + k * 1024); } while (0)
; #define PG8_BAR __builtin_amdgcn_s_barrier()
;     __device__ __forceinline__ void operator()(const f32x4 (&acc)[2][2][4][2], const Unit& u, int wr, int wc, int fr, int fq) const {
;     ...
;             for (int m = 0; m < 4; ++m) { const int row = u.pm * BM + ai * HALF + wr * 64 + m * 16 + fr; const size_t off = (size_t)row * ldc + col0;
;                 float ss = 0.f;
; #pragma unroll
;                 for (int bj = 0; bj < 2; ++bj)
; #pragma unroll
;                     for (int n = 0; n < 2; ++n) { f32x4 bs;
;                         if (BASE_BF16) { const u32x2 t = *(const u32x2*)((const bf16_t*)base + off + bj * HALF + n * 16);
;                             bs = (f32x4){__builtin_bit_cast(float, t.x << 16), __builtin_bit_cast(float, t.x & 0xffff0000u), __builtin_bit_cast(float, t.y << 16), __builtin_bit_cast(float, t.y & 0xffff0000u)}; }
;                         else bs = *(const f32x4*)((const float*)base + off + bj * HALF + n * 16);
; template <class Epi, class Sched, bool ALIGN_EPI = false, bool SP2 = false>
; __device__ __forceinline__ void gemm_phase(PG8_LAS unsigned char* lds, const Gemm g, const Sched& S, const Epi& E, int wave_in) {
;     ...
;             PG8_LDB(B0, 1, 0); PG8_LDB(B1, 1, 1); PG8_SCHED; PG8_LDA(At, 1, 0); PG8_STAGE(PG8_SA(0, 1), a2 + hstep, voffA);
;             PG8_WAIT_V(8); PG8_WAIT_L(0); PG8_BAR; PG8_MMA(0, 0, At, B0); PG8_MMA(0, 1, At, B1); PG8_BAR; PG8_SCHED;
;             PG8_LDA(At, 1, 1); PG8_STAGE(PG8_SB(1, 0), b3, voffB); PG8_STAGE(PG8_SB(1, 1), b3 + hstep, voffB); PG8_STAGE(PG8_SA(1, 0), a3, voffA);
;             PG8_WAIT_V(8); PG8_WAIT_L(0); PG8_BAR; PG8_MMA(1, 0, At, B0); PG8_MMA(1, 1, At, B1); PG8_BAR; PG8_SCHED;
	s_setprio 3
	v_mfma_f32_16x16x32_bf16 v[84:87], v[172:175], v[204:207], v[84:87]
	v_mfma_f32_16x16x32_bf16 v[80:83], v[180:183], v[204:207], v[80:83]
	v_mfma_f32_16x16x32_bf16 v[68:71], v[172:175], v[212:215], v[68:71]
	v_mfma_f32_16x16x32_bf16 v[64:67], v[180:183], v[212:215], v[64:67]
	s_setprio 0
	s_add_i32 s26, s56, s21
	v_lshl_add_u64 v[164:165], v[164:165], 0, s[10:11]
	s_mov_b32 m0, s26
	ds_read_b128 v[184:187], v149 offset:49152
	ds_read_b128 v[188:191], v149 offset:50176
	ds_read_b128 v[192:195], v149 offset:51200
	ds_read_b128 v[196:199], v149 offset:52224
	ds_read_b128 v[200:203], v149 offset:53248
	ds_read_b128 v[204:207], v149 offset:54272
	ds_read_b128 v[208:211], v149 offset:55296
	ds_read_b128 v[212:215], v149 offset:56320
	global_load_lds_dwordx4 v[164:165], off
	s_add_i32 m0, s26, 0x2000
	s_add_u32 s26, s30, 0x160080
	v_lshl_add_u64 v[164:165], v[166:167], 0, s[10:11]
	s_addc_u32 s27, s31, 0
	s_add_i32 s30, s57, s21
	global_load_lds_dwordx4 v[164:165], off
	v_lshl_add_u64 v[164:165], s[26:27], 0, v[128:129]
	s_mov_b32 m0, s30
	s_nop 0
	global_load_lds_dwordx4 v[164:165], off
	v_lshl_add_u64 v[164:165], s[26:27], 0, v[130:131]
	s_add_i32 m0, s30, 0x2000
	s_nop 0
	global_load_lds_dwordx4 v[164:165], off
	v_lshl_add_u64 v[164:165], v[216:217], 0, s[10:11]
	s_mov_b32 m0, s42
	s_nop 0
	global_load_lds_dwordx4 v[164:165], off
	v_lshl_add_u64 v[164:165], v[218:219], 0, s[10:11]
	s_mov_b32 m0, s43
	s_nop 0
	global_load_lds_dwordx4 v[164:165], off
	s_waitcnt vmcnt(8)
	s_waitcnt lgkmcnt(0)
	s_barrier
	s_setprio 1
	s_waitcnt lgkmcnt(0)
	v_mfma_f32_16x16x32_bf16 v[60:63], v[140:143], v[184:187], v[60:63]
	v_mfma_f32_16x16x32_bf16 v[56:59], v[156:159], v[184:187], v[56:59]
	v_mfma_f32_16x16x32_bf16 v[44:47], v[140:143], v[192:195], v[44:47]
	v_mfma_f32_16x16x32_bf16 v[40:43], v[156:159], v[192:195], v[40:43]
	v_mfma_f32_16x16x32_bf16 v[28:31], v[140:143], v[200:203], v[28:31]
	v_mfma_f32_16x16x32_bf16 v[24:27], v[156:159], v[200:203], v[24:27]
	v_mfma_f32_16x16x32_bf16 v[12:15], v[140:143], v[208:211], v[12:15]
	v_mfma_f32_16x16x32_bf16 v[8:11], v[156:159], v[208:211], v[8:11]
	v_mfma_f32_16x16x32_bf16 v[60:63], v[152:155], v[188:191], v[60:63]
	v_mfma_f32_16x16x32_bf16 v[56:59], v[160:163], v[188:191], v[56:59]
	v_mfma_f32_16x16x32_bf16 v[44:47], v[152:155], v[196:199], v[44:47]
	v_mfma_f32_16x16x32_bf16 v[40:43], v[160:163], v[196:199], v[40:43]
	v_mfma_f32_16x16x32_bf16 v[28:31], v[152:155], v[204:207], v[28:31]
	v_mfma_f32_16x16x32_bf16 v[24:27], v[160:163], v[204:207], v[24:27]
	v_mfma_f32_16x16x32_bf16 v[12:15], v[152:155], v[212:215], v[12:15]
	v_mfma_f32_16x16x32_bf16 v[8:11], v[160:163], v[212:215], v[8:11]
	s_setprio 0
	s_setprio 1
	v_mfma_f32_16x16x32_bf16 v[52:55], v[168:171], v[184:187], v[52:55]
	v_mfma_f32_16x16x32_bf16 v[48:51], v[176:179], v[184:187], v[48:51]
	v_mfma_f32_16x16x32_bf16 v[36:39], v[168:171], v[192:195], v[36:39]
	v_mfma_f32_16x16x32_bf16 v[32:35], v[176:179], v[192:195], v[32:35]
	v_mfma_f32_16x16x32_bf16 v[20:23], v[168:171], v[200:203], v[20:23]
	v_mfma_f32_16x16x32_bf16 v[16:19], v[176:179], v[200:203], v[16:19]
	v_mfma_f32_16x16x32_bf16 v[4:7], v[168:171], v[208:211], v[4:7]
	v_mfma_f32_16x16x32_bf16 v[0:3], v[176:179], v[208:211], v[0:3]
	v_mfma_f32_16x16x32_bf16 v[52:55], v[172:175], v[188:191], v[52:55]
	v_mfma_f32_16x16x32_bf16 v[48:51], v[180:183], v[188:191], v[48:51]
	v_mfma_f32_16x16x32_bf16 v[36:39], v[172:175], v[196:199], v[36:39]
	v_mfma_f32_16x16x32_bf16 v[32:35], v[180:183], v[196:199], v[32:35]
	s_barrier
	s_setprio 3
	v_mfma_f32_16x16x32_bf16 v[20:23], v[172:175], v[204:207], v[20:23]
	v_mfma_f32_16x16x32_bf16 v[16:19], v[180:183], v[204:207], v[16:19]
	v_mfma_f32_16x16x32_bf16 v[4:7], v[172:175], v[212:215], v[4:7]
	v_mfma_f32_16x16x32_bf16 v[0:3], v[180:183], v[212:215], v[0:3]
	s_setprio 0
	s_add_i32 s55, s55, 2
	s_add_u32 s53, s53, 0x100
	s_addc_u32 s54, s54, 0
	s_cmpk_gt_u32 s55, 0x55
	s_mov_b64 s[26:27], s[28:29]
	s_cbranch_scc0 .LBB0_307
	v_lshl_add_u32 v142, s51, 8, v144
	v_lshl_or_b32 v140, s52, 8, v146
	v_ashrrev_i32_e32 v143, 31, v142
	v_ashrrev_i32_e32 v141, 31, v140
	v_xor_b32_e32 v212, 16, v150
	v_xor_b32_e32 v213, 32, v150
	v_lshlrev_b32_e32 v212, 2, v212
	v_lshlrev_b32_e32 v213, 2, v213
	v_mov_b32_e32 v152, v142
	v_ashrrev_i32_e32 v153, 31, v152
	v_lshlrev_b64 v[154:155], 11, v[152:153]
	v_lshl_add_u64 v[154:155], v[154:155], 0, v[140:141]
	v_lshl_add_u64 v[156:157], v[154:155], 2, s[0:1]
	global_load_dwordx4 v[164:167], v[156:157], off nt
	global_load_dwordx4 v[168:171], v[156:157], off offset:64 nt
	global_load_dwordx4 v[172:175], v[156:157], off offset:512 nt
	global_load_dwordx4 v[176:179], v[156:157], off offset:576 nt
	v_add_u32_e32 v152, 16, v142
	v_ashrrev_i32_e32 v153, 31, v152
	v_lshlrev_b64 v[154:155], 11, v[152:153]
	v_lshl_add_u64 v[154:155], v[154:155], 0, v[140:141]
	v_lshl_add_u64 v[156:157], v[154:155], 2, s[0:1]
	global_load_dwordx4 v[180:183], v[156:157], off nt
	global_load_dwordx4 v[184:187], v[156:157], off offset:64 nt
	global_load_dwordx4 v[188:191], v[156:157], off offset:512 nt
	global_load_dwordx4 v[192:195], v[156:157], off offset:576 nt
	v_add_u32_e32 v152, 32, v142
	v_ashrrev_i32_e32 v153, 31, v152
	v_lshlrev_b64 v[154:155], 11, v[152:153]
	v_lshl_add_u64 v[154:155], v[154:155], 0, v[140:141]
	v_lshl_add_u64 v[156:157], v[154:155], 2, s[0:1]
	global_load_dwordx4 v[196:199], v[156:157], off nt
	global_load_dwordx4 v[200:203], v[156:157], off offset:64 nt
	global_load_dwordx4 v[204:207], v[156:157], off offset:512 nt
	global_load_dwordx4 v[208:211], v[156:157], off offset:576 nt
	s_and_b64 vcc, exec, s[18:19]
	s_cbranch_vccz .LBB0_310
	s_barrier
; __device__ __forceinline__ unsigned cvt_pk_bf16(float lo, float hi) { unsigned r; asm volatile("v_cvt_pk_bf16_f32 %0, %1, %2" : "=v"(r) : "v"(lo), "v"(hi)); return r; }
;     __device__ __forceinline__ void operator()(const f32x4 (&acc)[2][2][4][2], const Unit& u, int wr, int wc, int fr, int fq) const {
;     ...
;             for (int m = 0; m < 4; ++m) { const int row = u.pm * BM + ai * HALF + wr * 64 + m * 16 + fr; const size_t off = (size_t)row * ldc + col0;
;                 float ss = 0.f;
; #pragma unroll
;                 for (int bj = 0; bj < 2; ++bj)
; #pragma unroll
;                     for (int n = 0; n < 2; ++n) { f32x4 bs;
;                         if (BASE_BF16) { const u32x2 t = *(const u32x2*)((const bf16_t*)base + off + bj * HALF + n * 16);
;                             bs = (f32x4){__builtin_bit_cast(float, t.x << 16), __builtin_bit_cast(float, t.x & 0xffff0000u), __builtin_bit_cast(float, t.y << 16), __builtin_bit_cast(float, t.y & 0xffff0000u)}; }
;                         else bs = *(const f32x4*)((const float*)base + off + bj * HALF + n * 16);
;                         const f32x4 v = bs + acc[ai][bj][m][n] * scale;
;                         u32x2 w; w.x = cvt_pk_bf16(v[0], v[1]); w.y = cvt_pk_bf16(v[2], v[3]);
;                         *(u32x2*)(xn + off + bj * HALF + n * 16) = w;
;                         ss += (v[0] * v[0] + v[1] * v[1]) + (v[2] * v[2] + v[3] * v[3]); }
.LBB0_310:
	s_waitcnt vmcnt(8)
	v_pk_fma_f32 v[166:167], v[126:127], 0.5, v[166:167] op_sel_hi:[1,0,1]
	v_pk_fma_f32 v[164:165], v[124:125], 0.5, v[164:165] op_sel_hi:[1,0,1]
	v_pk_fma_f32 v[170:171], v[122:123], 0.5, v[170:171] op_sel_hi:[1,0,1]
	v_pk_fma_f32 v[168:169], v[120:121], 0.5, v[168:169] op_sel_hi:[1,0,1]
	v_pk_fma_f32 v[174:175], v[118:119], 0.5, v[174:175] op_sel_hi:[1,0,1]
	v_pk_fma_f32 v[172:173], v[116:117], 0.5, v[172:173] op_sel_hi:[1,0,1]
	v_pk_fma_f32 v[178:179], v[114:115], 0.5, v[178:179] op_sel_hi:[1,0,1]
	v_pk_fma_f32 v[176:177], v[112:113], 0.5, v[176:177] op_sel_hi:[1,0,1]
	v_mov_b32_e32 v214, v142
	v_ashrrev_i32_e32 v215, 31, v214
	v_lshlrev_b64 v[216:217], 11, v[214:215]
	v_lshl_add_u64 v[216:217], v[216:217], 0, v[140:141]
	v_lshl_add_u64 v[218:219], v[216:217], 1, s[76:77]
	v_cvt_pk_bf16_f32 v124, v164, v165
	v_cvt_pk_bf16_f32 v125, v166, v167
	global_store_dwordx2 v[218:219], v[124:125], off
	v_mul_f32_e32 v221, v165, v165
	v_mul_f32_e32 v162, v167, v167
	v_fmac_f32_e32 v221, v164, v164
	v_fmac_f32_e32 v162, v166, v166
	v_add_f32_e32 v220, v221, v162
	v_cvt_pk_bf16_f32 v120, v168, v169
	v_cvt_pk_bf16_f32 v121, v170, v171
	global_store_dwordx2 v[218:219], v[120:121], off offset:32
	v_mul_f32_e32 v221, v169, v169
	v_mul_f32_e32 v162, v171, v171
	v_fmac_f32_e32 v221, v168, v168
	v_fmac_f32_e32 v162, v170, v170
	v_add_f32_e32 v221, v221, v162
	v_add_f32_e32 v220, v220, v221
	v_cvt_pk_bf16_f32 v116, v172, v173
	v_cvt_pk_bf16_f32 v117, v174, v175
	global_store_dwordx2 v[218:219], v[116:117], off offset:256
	v_mul_f32_e32 v221, v173, v173
	v_mul_f32_e32 v162, v175, v175
	v_fmac_f32_e32 v221, v172, v172
	v_fmac_f32_e32 v162, v174, v174
	v_add_f32_e32 v221, v221, v162
	v_add_f32_e32 v220, v220, v221
	v_cvt_pk_bf16_f32 v112, v176, v177
	v_cvt_pk_bf16_f32 v113, v178, v179
	global_store_dwordx2 v[218:219], v[112:113], off offset:288
	v_mul_f32_e32 v221, v177, v177
	v_mul_f32_e32 v162, v179, v179
	v_fmac_f32_e32 v221, v176, v176
	v_fmac_f32_e32 v162, v178, v178
	v_add_f32_e32 v221, v221, v162
	v_add_f32_e32 v160, v220, v221
	v_add_u32_e32 v152, 48, v142
	v_ashrrev_i32_e32 v153, 31, v152
	v_lshlrev_b64 v[154:155], 11, v[152:153]
	v_lshl_add_u64 v[154:155], v[154:155], 0, v[140:141]
	v_lshl_add_u64 v[156:157], v[154:155], 2, s[0:1]
	global_load_dwordx4 v[112:115], v[156:157], off nt
	global_load_dwordx4 v[116:119], v[156:157], off offset:64 nt
	global_load_dwordx4 v[120:123], v[156:157], off offset:512 nt
	global_load_dwordx4 v[124:127], v[156:157], off offset:576 nt
	s_waitcnt vmcnt(12)
	v_pk_fma_f32 v[182:183], v[110:111], 0.5, v[182:183] op_sel_hi:[1,0,1]
	v_pk_fma_f32 v[180:181], v[108:109], 0.5, v[180:181] op_sel_hi:[1,0,1]
	v_pk_fma_f32 v[186:187], v[106:107], 0.5, v[186:187] op_sel_hi:[1,0,1]
	v_pk_fma_f32 v[184:185], v[104:105], 0.5, v[184:185] op_sel_hi:[1,0,1]
	v_pk_fma_f32 v[190:191], v[102:103], 0.5, v[190:191] op_sel_hi:[1,0,1]
	v_pk_fma_f32 v[188:189], v[100:101], 0.5, v[188:189] op_sel_hi:[1,0,1]
	v_pk_fma_f32 v[194:195], v[98:99], 0.5, v[194:195] op_sel_hi:[1,0,1]
	v_pk_fma_f32 v[192:193], v[96:97], 0.5, v[192:193] op_sel_hi:[1,0,1]
	v_add_u32_e32 v214, 16, v142
	v_ashrrev_i32_e32 v215, 31, v214
	v_lshlrev_b64 v[216:217], 11, v[214:215]
	v_lshl_add_u64 v[216:217], v[216:217], 0, v[140:141]
	v_lshl_add_u64 v[218:219], v[216:217], 1, s[76:77]
	v_cvt_pk_bf16_f32 v108, v180, v181
	v_cvt_pk_bf16_f32 v109, v182, v183
	global_store_dwordx2 v[218:219], v[108:109], off
	v_mul_f32_e32 v221, v181, v181
	v_mul_f32_e32 v162, v183, v183
	v_fmac_f32_e32 v221, v180, v180
	v_fmac_f32_e32 v162, v182, v182
	v_add_f32_e32 v220, v221, v162
	v_cvt_pk_bf16_f32 v104, v184, v185
	v_cvt_pk_bf16_f32 v105, v186, v187
	global_store_dwordx2 v[218:219], v[104:105], off offset:32
	v_mul_f32_e32 v221, v185, v185
	v_mul_f32_e32 v162, v187, v187
	v_fmac_f32_e32 v221, v184, v184
	v_fmac_f32_e32 v162, v186, v186
	v_add_f32_e32 v221, v221, v162
	v_add_f32_e32 v220, v220, v221
	v_cvt_pk_bf16_f32 v100, v188, v189
	v_cvt_pk_bf16_f32 v101, v190, v191
	global_store_dwordx2 v[218:219], v[100:101], off offset:256
	v_mul_f32_e32 v221, v189, v189
	v_mul_f32_e32 v162, v191, v191
	v_fmac_f32_e32 v221, v188, v188
	v_fmac_f32_e32 v162, v190, v190
	v_add_f32_e32 v221, v221, v162
	v_add_f32_e32 v220, v220, v221
	v_cvt_pk_bf16_f32 v96, v192, v193
	v_cvt_pk_bf16_f32 v97, v194, v195
	global_store_dwordx2 v[218:219], v[96:97], off offset:288
	v_mul_f32_e32 v221, v193, v193
	v_mul_f32_e32 v162, v195, v195
	v_fmac_f32_e32 v221, v192, v192
	v_fmac_f32_e32 v162, v194, v194
	v_add_f32_e32 v221, v221, v162
	v_add_f32_e32 v164, v220, v221
	v_add_u32_e32 v152, 0x80, v142
	v_ashrrev_i32_e32 v153, 31, v152
	v_lshlrev_b64 v[154:155], 11, v[152:153]
	v_lshl_add_u64 v[154:155], v[154:155], 0, v[140:141]
	v_lshl_add_u64 v[156:157], v[154:155], 2, s[0:1]
	global_load_dwordx4 v[96:99], v[156:157], off nt
	global_load_dwordx4 v[100:103], v[156:157], off offset:64 nt
	global_load_dwordx4 v[104:107], v[156:157], off offset:512 nt
	global_load_dwordx4 v[108:111], v[156:157], off offset:576 nt
	s_waitcnt vmcnt(16)
; __device__ __forceinline__ unsigned cvt_pk_bf16(float lo, float hi) { unsigned r; asm volatile("v_cvt_pk_bf16_f32 %0, %1, %2" : "=v"(r) : "v"(lo), "v"(hi)); return r; }
;     __device__ __forceinline__ void operator()(const f32x4 (&acc)[2][2][4][2], const Unit& u, int wr, int wc, int fr, int fq) const {
;     ...
;             for (int m = 0; m < 4; ++m) { const int row = u.pm * BM + ai * HALF + wr * 64 + m * 16 + fr; const size_t off = (size_t)row * ldc + col0;
;                 float ss = 0.f;
; #pragma unroll
;                 for (int bj = 0; bj < 2; ++bj)
; #pragma unroll
;                     for (int n = 0; n < 2; ++n) { f32x4 bs;
;                         if (BASE_BF16) { const u32x2 t = *(const u32x2*)((const bf16_t*)base + off + bj * HALF + n * 16);
;                             bs = (f32x4){__builtin_bit_cast(float, t.x << 16), __builtin_bit_cast(float, t.x & 0xffff0000u), __builtin_bit_cast(float, t.y << 16), __builtin_bit_cast(float, t.y & 0xffff0000u)}; }
;                         else bs = *(const f32x4*)((const float*)base + off + bj * HALF + n * 16);
;                         const f32x4 v = bs + acc[ai][bj][m][n] * scale;
;                         u32x2 w; w.x = cvt_pk_bf16(v[0], v[1]); w.y = cvt_pk_bf16(v[2], v[3]);
;                         *(u32x2*)(xn + off + bj * HALF + n * 16) = w;
;                         ss += (v[0] * v[0] + v[1] * v[1]) + (v[2] * v[2] + v[3] * v[3]); }
	v_pk_fma_f32 v[198:199], v[94:95], 0.5, v[198:199] op_sel_hi:[1,0,1]
	v_pk_fma_f32 v[196:197], v[92:93], 0.5, v[196:197] op_sel_hi:[1,0,1]
	v_pk_fma_f32 v[202:203], v[90:91], 0.5, v[202:203] op_sel_hi:[1,0,1]
	v_pk_fma_f32 v[200:201], v[88:89], 0.5, v[200:201] op_sel_hi:[1,0,1]
	v_pk_fma_f32 v[206:207], v[86:87], 0.5, v[206:207] op_sel_hi:[1,0,1]
	v_pk_fma_f32 v[204:205], v[84:85], 0.5, v[204:205] op_sel_hi:[1,0,1]
	v_pk_fma_f32 v[210:211], v[82:83], 0.5, v[210:211] op_sel_hi:[1,0,1]
	v_pk_fma_f32 v[208:209], v[80:81], 0.5, v[208:209] op_sel_hi:[1,0,1]
	v_add_u32_e32 v214, 32, v142
	v_ashrrev_i32_e32 v215, 31, v214
	v_lshlrev_b64 v[216:217], 11, v[214:215]
	v_lshl_add_u64 v[216:217], v[216:217], 0, v[140:141]
	v_lshl_add_u64 v[218:219], v[216:217], 1, s[76:77]
	v_cvt_pk_bf16_f32 v92, v196, v197
	v_cvt_pk_bf16_f32 v93, v198, v199
	global_store_dwordx2 v[218:219], v[92:93], off
	v_mul_f32_e32 v221, v197, v197
	v_mul_f32_e32 v162, v199, v199
	v_fmac_f32_e32 v221, v196, v196
	v_fmac_f32_e32 v162, v198, v198
	v_add_f32_e32 v220, v221, v162
	v_cvt_pk_bf16_f32 v88, v200, v201
	v_cvt_pk_bf16_f32 v89, v202, v203
	global_store_dwordx2 v[218:219], v[88:89], off offset:32
	v_mul_f32_e32 v221, v201, v201
	v_mul_f32_e32 v162, v203, v203
	v_fmac_f32_e32 v221, v200, v200
	v_fmac_f32_e32 v162, v202, v202
	v_add_f32_e32 v221, v221, v162
	v_add_f32_e32 v220, v220, v221
	v_cvt_pk_bf16_f32 v84, v204, v205
	v_cvt_pk_bf16_f32 v85, v206, v207
	global_store_dwordx2 v[218:219], v[84:85], off offset:256
	v_mul_f32_e32 v221, v205, v205
	v_mul_f32_e32 v162, v207, v207
	v_fmac_f32_e32 v221, v204, v204
	v_fmac_f32_e32 v162, v206, v206
	v_add_f32_e32 v221, v221, v162
	v_add_f32_e32 v220, v220, v221
	v_cvt_pk_bf16_f32 v80, v208, v209
	v_cvt_pk_bf16_f32 v81, v210, v211
	global_store_dwordx2 v[218:219], v[80:81], off offset:288
	v_mul_f32_e32 v221, v209, v209
	v_mul_f32_e32 v162, v211, v211
	v_fmac_f32_e32 v221, v208, v208
	v_fmac_f32_e32 v162, v210, v210
	v_add_f32_e32 v221, v221, v162
	v_add_f32_e32 v165, v220, v221
	v_add_u32_e32 v152, 0x90, v142
	v_ashrrev_i32_e32 v153, 31, v152
	v_lshlrev_b64 v[154:155], 11, v[152:153]
	v_lshl_add_u64 v[154:155], v[154:155], 0, v[140:141]
	v_lshl_add_u64 v[156:157], v[154:155], 2, s[0:1]
	global_load_dwordx4 v[80:83], v[156:157], off nt
	global_load_dwordx4 v[84:87], v[156:157], off offset:64 nt
	global_load_dwordx4 v[88:91], v[156:157], off offset:512 nt
	global_load_dwordx4 v[92:95], v[156:157], off offset:576 nt
	s_waitcnt vmcnt(16)
	v_pk_fma_f32 v[114:115], v[78:79], 0.5, v[114:115] op_sel_hi:[1,0,1]
	v_pk_fma_f32 v[112:113], v[76:77], 0.5, v[112:113] op_sel_hi:[1,0,1]
	v_pk_fma_f32 v[118:119], v[74:75], 0.5, v[118:119] op_sel_hi:[1,0,1]
	v_pk_fma_f32 v[116:117], v[72:73], 0.5, v[116:117] op_sel_hi:[1,0,1]
	v_pk_fma_f32 v[122:123], v[70:71], 0.5, v[122:123] op_sel_hi:[1,0,1]
	v_pk_fma_f32 v[120:121], v[68:69], 0.5, v[120:121] op_sel_hi:[1,0,1]
	v_pk_fma_f32 v[126:127], v[66:67], 0.5, v[126:127] op_sel_hi:[1,0,1]
	v_pk_fma_f32 v[124:125], v[64:65], 0.5, v[124:125] op_sel_hi:[1,0,1]
	v_add_u32_e32 v214, 48, v142
	v_ashrrev_i32_e32 v215, 31, v214
	v_lshlrev_b64 v[216:217], 11, v[214:215]
	v_lshl_add_u64 v[216:217], v[216:217], 0, v[140:141]
	v_lshl_add_u64 v[218:219], v[216:217], 1, s[76:77]
	v_cvt_pk_bf16_f32 v76, v112, v113
	v_cvt_pk_bf16_f32 v77, v114, v115
	global_store_dwordx2 v[218:219], v[76:77], off
	v_mul_f32_e32 v221, v113, v113
	v_mul_f32_e32 v162, v115, v115
	v_fmac_f32_e32 v221, v112, v112
	v_fmac_f32_e32 v162, v114, v114
	v_add_f32_e32 v220, v221, v162
	v_cvt_pk_bf16_f32 v72, v116, v117
	v_cvt_pk_bf16_f32 v73, v118, v119
	global_store_dwordx2 v[218:219], v[72:73], off offset:32
	v_mul_f32_e32 v221, v117, v117
	v_mul_f32_e32 v162, v119, v119
	v_fmac_f32_e32 v221, v116, v116
	v_fmac_f32_e32 v162, v118, v118
	v_add_f32_e32 v221, v221, v162
	v_add_f32_e32 v220, v220, v221
	v_cvt_pk_bf16_f32 v68, v120, v121
	v_cvt_pk_bf16_f32 v69, v122, v123
	global_store_dwordx2 v[218:219], v[68:69], off offset:256
	v_mul_f32_e32 v221, v121, v121
	v_mul_f32_e32 v162, v123, v123
	v_fmac_f32_e32 v221, v120, v120
	v_fmac_f32_e32 v162, v122, v122
	v_add_f32_e32 v221, v221, v162
	v_add_f32_e32 v220, v220, v221
	v_cvt_pk_bf16_f32 v64, v124, v125
	v_cvt_pk_bf16_f32 v65, v126, v127
	global_store_dwordx2 v[218:219], v[64:65], off offset:288
	v_mul_f32_e32 v221, v125, v125
	v_mul_f32_e32 v162, v127, v127
	v_fmac_f32_e32 v221, v124, v124
	v_fmac_f32_e32 v162, v126, v126
	v_add_f32_e32 v221, v221, v162
	v_add_f32_e32 v166, v220, v221
	v_add_u32_e32 v152, 0xa0, v142
	v_ashrrev_i32_e32 v153, 31, v152
	v_lshlrev_b64 v[154:155], 11, v[152:153]
	v_lshl_add_u64 v[154:155], v[154:155], 0, v[140:141]
	v_lshl_add_u64 v[156:157], v[154:155], 2, s[0:1]
	global_load_dwordx4 v[64:67], v[156:157], off nt
	global_load_dwordx4 v[68:71], v[156:157], off offset:64 nt
	global_load_dwordx4 v[72:75], v[156:157], off offset:512 nt
	global_load_dwordx4 v[76:79], v[156:157], off offset:576 nt
	s_waitcnt vmcnt(16)
; __device__ __forceinline__ unsigned cvt_pk_bf16(float lo, float hi) { unsigned r; asm volatile("v_cvt_pk_bf16_f32 %0, %1, %2" : "=v"(r) : "v"(lo), "v"(hi)); return r; }
;     __device__ __forceinline__ void operator()(const f32x4 (&acc)[2][2][4][2], const Unit& u, int wr, int wc, int fr, int fq) const {
;     ...
;             for (int m = 0; m < 4; ++m) { const int row = u.pm * BM + ai * HALF + wr * 64 + m * 16 + fr; const size_t off = (size_t)row * ldc + col0;
;                 float ss = 0.f;
; #pragma unroll
;                 for (int bj = 0; bj < 2; ++bj)
; #pragma unroll
;                     for (int n = 0; n < 2; ++n) { f32x4 bs;
;                         if (BASE_BF16) { const u32x2 t = *(const u32x2*)((const bf16_t*)base + off + bj * HALF + n * 16);
;                             bs = (f32x4){__builtin_bit_cast(float, t.x << 16), __builtin_bit_cast(float, t.x & 0xffff0000u), __builtin_bit_cast(float, t.y << 16), __builtin_bit_cast(float, t.y & 0xffff0000u)}; }
;                         else bs = *(const f32x4*)((const float*)base + off + bj * HALF + n * 16);
;                         const f32x4 v = bs + acc[ai][bj][m][n] * scale;
;                         u32x2 w; w.x = cvt_pk_bf16(v[0], v[1]); w.y = cvt_pk_bf16(v[2], v[3]);
;                         *(u32x2*)(xn + off + bj * HALF + n * 16) = w;
;                         ss += (v[0] * v[0] + v[1] * v[1]) + (v[2] * v[2] + v[3] * v[3]); }
	v_pk_fma_f32 v[98:99], v[62:63], 0.5, v[98:99] op_sel_hi:[1,0,1]
	v_pk_fma_f32 v[96:97], v[60:61], 0.5, v[96:97] op_sel_hi:[1,0,1]
	v_pk_fma_f32 v[102:103], v[58:59], 0.5, v[102:103] op_sel_hi:[1,0,1]
	v_pk_fma_f32 v[100:101], v[56:57], 0.5, v[100:101] op_sel_hi:[1,0,1]
	v_pk_fma_f32 v[106:107], v[54:55], 0.5, v[106:107] op_sel_hi:[1,0,1]
	v_pk_fma_f32 v[104:105], v[52:53], 0.5, v[104:105] op_sel_hi:[1,0,1]
	v_pk_fma_f32 v[110:111], v[50:51], 0.5, v[110:111] op_sel_hi:[1,0,1]
	v_pk_fma_f32 v[108:109], v[48:49], 0.5, v[108:109] op_sel_hi:[1,0,1]
	v_add_u32_e32 v214, 0x80, v142
	v_ashrrev_i32_e32 v215, 31, v214
	v_lshlrev_b64 v[216:217], 11, v[214:215]
	v_lshl_add_u64 v[216:217], v[216:217], 0, v[140:141]
	v_lshl_add_u64 v[218:219], v[216:217], 1, s[76:77]
	v_cvt_pk_bf16_f32 v60, v96, v97
	v_cvt_pk_bf16_f32 v61, v98, v99
	global_store_dwordx2 v[218:219], v[60:61], off
	v_mul_f32_e32 v221, v97, v97
	v_mul_f32_e32 v162, v99, v99
	v_fmac_f32_e32 v221, v96, v96
	v_fmac_f32_e32 v162, v98, v98
	v_add_f32_e32 v220, v221, v162
	v_cvt_pk_bf16_f32 v56, v100, v101
	v_cvt_pk_bf16_f32 v57, v102, v103
	global_store_dwordx2 v[218:219], v[56:57], off offset:32
	v_mul_f32_e32 v221, v101, v101
	v_mul_f32_e32 v162, v103, v103
	v_fmac_f32_e32 v221, v100, v100
	v_fmac_f32_e32 v162, v102, v102
	v_add_f32_e32 v221, v221, v162
	v_add_f32_e32 v220, v220, v221
	v_cvt_pk_bf16_f32 v52, v104, v105
	v_cvt_pk_bf16_f32 v53, v106, v107
	global_store_dwordx2 v[218:219], v[52:53], off offset:256
	v_mul_f32_e32 v221, v105, v105
	v_mul_f32_e32 v162, v107, v107
	v_fmac_f32_e32 v221, v104, v104
	v_fmac_f32_e32 v162, v106, v106
	v_add_f32_e32 v221, v221, v162
	v_add_f32_e32 v220, v220, v221
	v_cvt_pk_bf16_f32 v48, v108, v109
	v_cvt_pk_bf16_f32 v49, v110, v111
	global_store_dwordx2 v[218:219], v[48:49], off offset:288
	v_mul_f32_e32 v221, v109, v109
	v_mul_f32_e32 v162, v111, v111
	v_fmac_f32_e32 v221, v108, v108
	v_fmac_f32_e32 v162, v110, v110
	v_add_f32_e32 v221, v221, v162
	v_add_f32_e32 v167, v220, v221
	v_add_u32_e32 v152, 0xb0, v142
	v_ashrrev_i32_e32 v153, 31, v152
	v_lshlrev_b64 v[154:155], 11, v[152:153]
	v_lshl_add_u64 v[154:155], v[154:155], 0, v[140:141]
	v_lshl_add_u64 v[156:157], v[154:155], 2, s[0:1]
	global_load_dwordx4 v[48:51], v[156:157], off nt
	global_load_dwordx4 v[52:55], v[156:157], off offset:64 nt
	global_load_dwordx4 v[56:59], v[156:157], off offset:512 nt
	global_load_dwordx4 v[60:63], v[156:157], off offset:576 nt
	s_waitcnt vmcnt(16)
	v_pk_fma_f32 v[82:83], v[46:47], 0.5, v[82:83] op_sel_hi:[1,0,1]
	v_pk_fma_f32 v[80:81], v[44:45], 0.5, v[80:81] op_sel_hi:[1,0,1]
	v_pk_fma_f32 v[86:87], v[42:43], 0.5, v[86:87] op_sel_hi:[1,0,1]
	v_pk_fma_f32 v[84:85], v[40:41], 0.5, v[84:85] op_sel_hi:[1,0,1]
	v_pk_fma_f32 v[90:91], v[38:39], 0.5, v[90:91] op_sel_hi:[1,0,1]
	v_pk_fma_f32 v[88:89], v[36:37], 0.5, v[88:89] op_sel_hi:[1,0,1]
	v_pk_fma_f32 v[94:95], v[34:35], 0.5, v[94:95] op_sel_hi:[1,0,1]
	v_pk_fma_f32 v[92:93], v[32:33], 0.5, v[92:93] op_sel_hi:[1,0,1]
	v_add_u32_e32 v214, 0x90, v142
	v_ashrrev_i32_e32 v215, 31, v214
	v_lshlrev_b64 v[216:217], 11, v[214:215]
	v_lshl_add_u64 v[216:217], v[216:217], 0, v[140:141]
	v_lshl_add_u64 v[218:219], v[216:217], 1, s[76:77]
	v_cvt_pk_bf16_f32 v44, v80, v81
	v_cvt_pk_bf16_f32 v45, v82, v83
	global_store_dwordx2 v[218:219], v[44:45], off
	v_mul_f32_e32 v221, v81, v81
	v_mul_f32_e32 v162, v83, v83
	v_fmac_f32_e32 v221, v80, v80
	v_fmac_f32_e32 v162, v82, v82
	v_add_f32_e32 v220, v221, v162
	v_cvt_pk_bf16_f32 v40, v84, v85
	v_cvt_pk_bf16_f32 v41, v86, v87
	global_store_dwordx2 v[218:219], v[40:41], off offset:32
	v_mul_f32_e32 v221, v85, v85
	v_mul_f32_e32 v162, v87, v87
	v_fmac_f32_e32 v221, v84, v84
	v_fmac_f32_e32 v162, v86, v86
	v_add_f32_e32 v221, v221, v162
	v_add_f32_e32 v220, v220, v221
	v_cvt_pk_bf16_f32 v36, v88, v89
	v_cvt_pk_bf16_f32 v37, v90, v91
	global_store_dwordx2 v[218:219], v[36:37], off offset:256
	v_mul_f32_e32 v221, v89, v89
	v_mul_f32_e32 v162, v91, v91
	v_fmac_f32_e32 v221, v88, v88
	v_fmac_f32_e32 v162, v90, v90
	v_add_f32_e32 v221, v221, v162
	v_add_f32_e32 v220, v220, v221
	v_cvt_pk_bf16_f32 v32, v92, v93
	v_cvt_pk_bf16_f32 v33, v94, v95
	global_store_dwordx2 v[218:219], v[32:33], off offset:288
	v_mul_f32_e32 v221, v93, v93
	v_mul_f32_e32 v162, v95, v95
	v_fmac_f32_e32 v221, v92, v92
	v_fmac_f32_e32 v162, v94, v94
	v_add_f32_e32 v221, v221, v162
	v_add_f32_e32 v168, v220, v221
	s_waitcnt vmcnt(12)
	v_pk_fma_f32 v[66:67], v[30:31], 0.5, v[66:67] op_sel_hi:[1,0,1]
	v_pk_fma_f32 v[64:65], v[28:29], 0.5, v[64:65] op_sel_hi:[1,0,1]
	v_pk_fma_f32 v[70:71], v[26:27], 0.5, v[70:71] op_sel_hi:[1,0,1]
	v_pk_fma_f32 v[68:69], v[24:25], 0.5, v[68:69] op_sel_hi:[1,0,1]
	v_pk_fma_f32 v[74:75], v[22:23], 0.5, v[74:75] op_sel_hi:[1,0,1]
	v_pk_fma_f32 v[72:73], v[20:21], 0.5, v[72:73] op_sel_hi:[1,0,1]
	v_pk_fma_f32 v[78:79], v[18:19], 0.5, v[78:79] op_sel_hi:[1,0,1]
	v_pk_fma_f32 v[76:77], v[16:17], 0.5, v[76:77] op_sel_hi:[1,0,1]
	v_add_u32_e32 v214, 0xa0, v142
	v_ashrrev_i32_e32 v215, 31, v214
	v_lshlrev_b64 v[216:217], 11, v[214:215]
	v_lshl_add_u64 v[216:217], v[216:217], 0, v[140:141]
	v_lshl_add_u64 v[218:219], v[216:217], 1, s[76:77]
	v_cvt_pk_bf16_f32 v28, v64, v65
	v_cvt_pk_bf16_f32 v29, v66, v67
	global_store_dwordx2 v[218:219], v[28:29], off
	v_mul_f32_e32 v221, v65, v65
	v_mul_f32_e32 v162, v67, v67
	v_fmac_f32_e32 v221, v64, v64
	v_fmac_f32_e32 v162, v66, v66
	v_add_f32_e32 v220, v221, v162
	v_cvt_pk_bf16_f32 v24, v68, v69
	v_cvt_pk_bf16_f32 v25, v70, v71
	global_store_dwordx2 v[218:219], v[24:25], off offset:32
	v_mul_f32_e32 v221, v69, v69
	v_mul_f32_e32 v162, v71, v71
	v_fmac_f32_e32 v221, v68, v68
	v_fmac_f32_e32 v162, v70, v70
	v_add_f32_e32 v221, v221, v162
	v_add_f32_e32 v220, v220, v221
	v_cvt_pk_bf16_f32 v20, v72, v73
	v_cvt_pk_bf16_f32 v21, v74, v75
	global_store_dwordx2 v[218:219], v[20:21], off offset:256
	v_mul_f32_e32 v221, v73, v73
	v_mul_f32_e32 v162, v75, v75
	v_fmac_f32_e32 v221, v72, v72
	v_fmac_f32_e32 v162, v74, v74
	v_add_f32_e32 v221, v221, v162
	v_add_f32_e32 v220, v220, v221
	v_cvt_pk_bf16_f32 v16, v76, v77
	v_cvt_pk_bf16_f32 v17, v78, v79
	global_store_dwordx2 v[218:219], v[16:17], off offset:288
	v_mul_f32_e32 v221, v77, v77
	v_mul_f32_e32 v162, v79, v79
	v_fmac_f32_e32 v221, v76, v76
	v_fmac_f32_e32 v162, v78, v78
	v_add_f32_e32 v221, v221, v162
	v_add_f32_e32 v169, v220, v221
	s_waitcnt vmcnt(8)
; __device__ __forceinline__ unsigned cvt_pk_bf16(float lo, float hi) { unsigned r; asm volatile("v_cvt_pk_bf16_f32 %0, %1, %2" : "=v"(r) : "v"(lo), "v"(hi)); return r; }
;     __device__ __forceinline__ void operator()(const f32x4 (&acc)[2][2][4][2], const Unit& u, int wr, int wc, int fr, int fq) const {
;     ...
;             for (int m = 0; m < 4; ++m) { const int row = u.pm * BM + ai * HALF + wr * 64 + m * 16 + fr; const size_t off = (size_t)row * ldc + col0;
;                 float ss = 0.f;
; #pragma unroll
;                 for (int bj = 0; bj < 2; ++bj)
; #pragma unroll
;                     for (int n = 0; n < 2; ++n) { f32x4 bs;
;                         if (BASE_BF16) { const u32x2 t = *(const u32x2*)((const bf16_t*)base + off + bj * HALF + n * 16);
;                             bs = (f32x4){__builtin_bit_cast(float, t.x << 16), __builtin_bit_cast(float, t.x & 0xffff0000u), __builtin_bit_cast(float, t.y << 16), __builtin_bit_cast(float, t.y & 0xffff0000u)}; }
;                         else bs = *(const f32x4*)((const float*)base + off + bj * HALF + n * 16);
;                         const f32x4 v = bs + acc[ai][bj][m][n] * scale;
;                         u32x2 w; w.x = cvt_pk_bf16(v[0], v[1]); w.y = cvt_pk_bf16(v[2], v[3]);
;                         *(u32x2*)(xn + off + bj * HALF + n * 16) = w;
;                         ss += (v[0] * v[0] + v[1] * v[1]) + (v[2] * v[2] + v[3] * v[3]); }
;                 ss += __shfl_xor(ss, 16); ss += __shfl_xor(ss, 32);
;                 if (fq == 0) __hip_atomic_fetch_add(rowss + row, ss, __ATOMIC_RELAXED, __HIP_MEMORY_SCOPE_AGENT); }
	v_pk_fma_f32 v[50:51], v[14:15], 0.5, v[50:51] op_sel_hi:[1,0,1]
	v_pk_fma_f32 v[48:49], v[12:13], 0.5, v[48:49] op_sel_hi:[1,0,1]
	v_pk_fma_f32 v[54:55], v[10:11], 0.5, v[54:55] op_sel_hi:[1,0,1]
	v_pk_fma_f32 v[52:53], v[8:9], 0.5, v[52:53] op_sel_hi:[1,0,1]
	v_pk_fma_f32 v[58:59], v[6:7], 0.5, v[58:59] op_sel_hi:[1,0,1]
	v_pk_fma_f32 v[56:57], v[4:5], 0.5, v[56:57] op_sel_hi:[1,0,1]
	v_pk_fma_f32 v[62:63], v[2:3], 0.5, v[62:63] op_sel_hi:[1,0,1]
	v_pk_fma_f32 v[60:61], v[0:1], 0.5, v[60:61] op_sel_hi:[1,0,1]
	v_add_u32_e32 v214, 0xb0, v142
	v_ashrrev_i32_e32 v215, 31, v214
	v_lshlrev_b64 v[216:217], 11, v[214:215]
	v_lshl_add_u64 v[216:217], v[216:217], 0, v[140:141]
	v_lshl_add_u64 v[218:219], v[216:217], 1, s[76:77]
	v_cvt_pk_bf16_f32 v12, v48, v49
	v_cvt_pk_bf16_f32 v13, v50, v51
	global_store_dwordx2 v[218:219], v[12:13], off
	v_mul_f32_e32 v221, v49, v49
	v_mul_f32_e32 v162, v51, v51
	v_fmac_f32_e32 v221, v48, v48
	v_fmac_f32_e32 v162, v50, v50
	v_add_f32_e32 v220, v221, v162
	v_cvt_pk_bf16_f32 v8, v52, v53
	v_cvt_pk_bf16_f32 v9, v54, v55
	global_store_dwordx2 v[218:219], v[8:9], off offset:32
	v_mul_f32_e32 v221, v53, v53
	v_mul_f32_e32 v162, v55, v55
	v_fmac_f32_e32 v221, v52, v52
	v_fmac_f32_e32 v162, v54, v54
	v_add_f32_e32 v221, v221, v162
	v_add_f32_e32 v220, v220, v221
	v_cvt_pk_bf16_f32 v4, v56, v57
	v_cvt_pk_bf16_f32 v5, v58, v59
	global_store_dwordx2 v[218:219], v[4:5], off offset:256
	v_mul_f32_e32 v221, v57, v57
	v_mul_f32_e32 v162, v59, v59
	v_fmac_f32_e32 v221, v56, v56
	v_fmac_f32_e32 v162, v58, v58
	v_add_f32_e32 v221, v221, v162
	v_add_f32_e32 v220, v220, v221
	v_cvt_pk_bf16_f32 v0, v60, v61
	v_cvt_pk_bf16_f32 v1, v62, v63
	global_store_dwordx2 v[218:219], v[0:1], off offset:288
	v_mul_f32_e32 v221, v61, v61
	v_mul_f32_e32 v162, v63, v63
	v_fmac_f32_e32 v221, v60, v60
	v_fmac_f32_e32 v162, v62, v62
	v_add_f32_e32 v221, v221, v162
	v_add_f32_e32 v170, v220, v221
	ds_bpermute_b32 v172, v212, v160
	ds_bpermute_b32 v173, v212, v164
	ds_bpermute_b32 v174, v212, v165
	ds_bpermute_b32 v175, v212, v166
	ds_bpermute_b32 v176, v212, v167
	ds_bpermute_b32 v177, v212, v168
	ds_bpermute_b32 v178, v212, v169
	ds_bpermute_b32 v179, v212, v170
	s_waitcnt lgkmcnt(0)
	v_add_f32_e32 v160, v160, v172
	v_add_f32_e32 v164, v164, v173
	v_add_f32_e32 v165, v165, v174
	v_add_f32_e32 v166, v166, v175
	v_add_f32_e32 v167, v167, v176
	v_add_f32_e32 v168, v168, v177
	v_add_f32_e32 v169, v169, v178
	v_add_f32_e32 v170, v170, v179
	ds_bpermute_b32 v172, v213, v160
	ds_bpermute_b32 v173, v213, v164
	ds_bpermute_b32 v174, v213, v165
	ds_bpermute_b32 v175, v213, v166
	ds_bpermute_b32 v176, v213, v167
	ds_bpermute_b32 v177, v213, v168
	ds_bpermute_b32 v178, v213, v169
	ds_bpermute_b32 v179, v213, v170
	s_waitcnt lgkmcnt(0)
	v_add_f32_e32 v160, v160, v172
	v_add_f32_e32 v164, v164, v173
	v_add_f32_e32 v165, v165, v174
	v_add_f32_e32 v166, v166, v175
	v_add_f32_e32 v167, v167, v176
	v_add_f32_e32 v168, v168, v177
	v_add_f32_e32 v169, v169, v178
	v_add_f32_e32 v170, v170, v179
	v_mul_f32_e32 v160, 0x43000000, v160
	v_mul_f32_e32 v164, 0x43000000, v164
	v_mul_f32_e32 v165, 0x43000000, v165
	v_mul_f32_e32 v166, 0x43000000, v166
	v_mul_f32_e32 v167, 0x43000000, v167
	v_mul_f32_e32 v168, 0x43000000, v168
	v_mul_f32_e32 v169, 0x43000000, v169
	v_mul_f32_e32 v170, 0x43000000, v170
	v_rndne_f32_e32 v160, v160
	v_rndne_f32_e32 v164, v164
	v_rndne_f32_e32 v165, v165
	v_rndne_f32_e32 v166, v166
	v_rndne_f32_e32 v167, v167
	v_rndne_f32_e32 v168, v168
	v_rndne_f32_e32 v169, v169
	v_rndne_f32_e32 v170, v170
	v_mul_f32_e32 v160, 0x3c000000, v160
	v_mul_f32_e32 v164, 0x3c000000, v164
	v_mul_f32_e32 v165, 0x3c000000, v165
	v_mul_f32_e32 v166, 0x3c000000, v166
	v_mul_f32_e32 v167, 0x3c000000, v167
	v_mul_f32_e32 v168, 0x3c000000, v168
	v_mul_f32_e32 v169, 0x3c000000, v169
	v_mul_f32_e32 v170, 0x3c000000, v170
	s_and_saveexec_b64 s[26:27], s[6:7]
	v_mov_b32_e32 v214, v142
	v_ashrrev_i32_e32 v215, 31, v214
	v_lshl_add_u64 v[216:217], v[214:215], 2, s[16:17]
	global_atomic_add_f32 v[216:217], v160, off
	v_add_u32_e32 v214, 16, v142
	v_ashrrev_i32_e32 v215, 31, v214
	v_lshl_add_u64 v[216:217], v[214:215], 2, s[16:17]
	global_atomic_add_f32 v[216:217], v164, off
	v_add_u32_e32 v214, 32, v142
	v_ashrrev_i32_e32 v215, 31, v214
	v_lshl_add_u64 v[216:217], v[214:215], 2, s[16:17]
	global_atomic_add_f32 v[216:217], v165, off
	v_add_u32_e32 v214, 48, v142
	v_ashrrev_i32_e32 v215, 31, v214
	v_lshl_add_u64 v[216:217], v[214:215], 2, s[16:17]
	global_atomic_add_f32 v[216:217], v166, off
	v_add_u32_e32 v214, 0x80, v142
	v_ashrrev_i32_e32 v215, 31, v214
	v_lshl_add_u64 v[216:217], v[214:215], 2, s[16:17]
	global_atomic_add_f32 v[216:217], v167, off
	v_add_u32_e32 v214, 0x90, v142
	v_ashrrev_i32_e32 v215, 31, v214
	v_lshl_add_u64 v[216:217], v[214:215], 2, s[16:17]
	global_atomic_add_f32 v[216:217], v168, off
	v_add_u32_e32 v214, 0xa0, v142
	v_ashrrev_i32_e32 v215, 31, v214
	v_lshl_add_u64 v[216:217], v[214:215], 2, s[16:17]
	global_atomic_add_f32 v[216:217], v169, off
	v_add_u32_e32 v214, 0xb0, v142
	v_ashrrev_i32_e32 v215, 31, v214
	v_lshl_add_u64 v[216:217], v[214:215], 2, s[16:17]
	global_atomic_add_f32 v[216:217], v170, off
	s_or_b64 exec, exec, s[26:27]
	s_and_b64 vcc, exec, s[8:9]
	s_mov_b64 s[8:9], -1
	s_cbranch_vccnz .LBB0_295
	s_andn2_b64 vcc, exec, s[2:3]
	s_cbranch_vccnz .LBB0_294
	s_barrier
	s_branch .LBB0_294

; #define LAS __attribute__((address_space(3)))
; __device__ __forceinline__ unsigned cvtpk(float lo, float hi) { f32x2 v = {lo, hi}; bf16x2_t b = __builtin_convertvector(v, bf16x2_t); return __builtin_bit_cast(unsigned, b); }
; __device__ __forceinline__ void gla_scan(const Params& p, LAS unsigned char* lds, int wave) {
;     ...
;         for (int cb = 0; cb < 4; ++cb) {
;             u32x2 uu[16];
; #pragma unroll
;             for (int i = 0; i < 16; ++i) { const int cn = 16 * cb + i + 1; const int cl = cn < 64 ? cn : 63; uu[i] = base[(size_t)cl * 8192]; }
; #pragma unroll
;             for (int i = 0; i < 16; ++i) { const int cn = 16 * cb + i + 1;
;                 if (cn < 64) {
;                     const f32x4 e3 = *(const LAS f32x4*)(lds + 32768 + ((cn - 1) * 128 + dk) * 4), e1 = *(const LAS f32x4*)(lds + (cn * 128 + dk) * 4);
;                     const f32x4 uf = (f32x4){bflo(ucur.x), bfhi(ucur.x), bflo(ucur.y), bfhi(ucur.y)};
;                     s = e3 * s + uf;
;                     const f32x4 o = e1 * s; u32x2 w; w.x = cvtpk(o[0], o[1]); w.y = cvtpk(o[2], o[3]);
;                     base[(size_t)cn * 8192] = w; ucur = uu[i]; } }
.LBB0_664:
	v_lshl_add_u64 v[20:21], v[18:19], 0, s[2:3]
	v_add_co_u32_e32 v58, vcc, 0x1b120000, v20
	s_mov_b64 s[4:5], vcc
	v_add_co_u32_e32 v54, vcc, 0x1b130000, v20
	s_mov_b64 s[6:7], vcc
	v_add_co_u32_e32 v52, vcc, 0x1b140000, v20
	s_mov_b64 s[8:9], vcc
	v_add_co_u32_e32 v48, vcc, 0x1b150000, v20
	s_mov_b64 s[10:11], vcc
	v_add_co_u32_e32 v46, vcc, 0x1b160000, v20
	s_mov_b64 s[12:13], vcc
	v_add_co_u32_e32 v44, vcc, 0x1b170000, v20
	s_mov_b64 s[14:15], vcc
	v_add_co_u32_e32 v42, vcc, 0x1b180000, v20
	s_mov_b64 s[16:17], vcc
	v_add_co_u32_e32 v40, vcc, 0x1b190000, v20
	s_mov_b64 s[18:19], vcc
	v_add_co_u32_e32 v36, vcc, 0x1b1a0000, v20
	s_mov_b64 s[20:21], vcc
	v_add_co_u32_e32 v34, vcc, 0x1b1b0000, v20
	s_mov_b64 s[22:23], vcc
	v_add_co_u32_e32 v32, vcc, 0x1b1c0000, v20
	s_mov_b64 s[24:25], vcc
	v_add_co_u32_e32 v30, vcc, 0x1b1d0000, v20
	s_min_u32 s0, s41, 62
	s_mov_b64 s[26:27], vcc
	v_add_co_u32_e32 v26, vcc, 0x1b1e0000, v20
	s_lshl_b32 s0, s0, 16
	s_mov_b64 s[28:29], vcc
	v_add_co_u32_e32 v24, vcc, 0x1b1f0000, v20
	v_lshl_add_u64 v[6:7], v[16:17], 0, s[0:1]
	s_mov_b64 s[30:31], vcc
	v_add_co_u32_e32 v6, vcc, 0x10000, v6
	s_mov_b64 s[34:35], vcc
	v_add_co_u32_e32 v80, vcc, 0x1b110000, v20
	v_addc_co_u32_e32 v81, vcc, 0, v21, vcc
	global_load_dwordx2 v[82:83], v[80:81], off
	v_addc_co_u32_e64 v59, vcc, 0, v21, s[4:5]
	global_load_dwordx2 v[78:79], v[58:59], off
	v_addc_co_u32_e64 v55, vcc, 0, v21, s[6:7]
	global_load_dwordx2 v[76:77], v[54:55], off
	v_addc_co_u32_e64 v27, vcc, 0, v21, s[28:29]
	v_addc_co_u32_e64 v53, vcc, 0, v21, s[8:9]
	v_addc_co_u32_e64 v25, vcc, 0, v21, s[30:31]
	v_addc_co_u32_e64 v7, vcc, 0, v7, s[34:35]
	global_load_dwordx2 v[38:39], v[26:27], off
	global_load_dwordx2 v[28:29], v[24:25], off
	global_load_dwordx2 v[22:23], v[6:7], off
	v_addc_co_u32_e64 v49, vcc, 0, v21, s[10:11]
	global_load_dwordx2 v[74:75], v[52:53], off
	global_load_dwordx2 v[72:73], v[48:49], off
	v_addc_co_u32_e64 v47, vcc, 0, v21, s[12:13]
	v_addc_co_u32_e64 v45, vcc, 0, v21, s[14:15]
	v_addc_co_u32_e64 v43, vcc, 0, v21, s[16:17]
	v_addc_co_u32_e64 v41, vcc, 0, v21, s[18:19]
	global_load_dwordx2 v[70:71], v[46:47], off
	global_load_dwordx2 v[68:69], v[44:45], off
	global_load_dwordx2 v[66:67], v[42:43], off
	global_load_dwordx2 v[64:65], v[40:41], off
	v_addc_co_u32_e64 v37, vcc, 0, v21, s[20:21]
	v_addc_co_u32_e64 v35, vcc, 0, v21, s[22:23]
	v_addc_co_u32_e64 v33, vcc, 0, v21, s[24:25]
	v_addc_co_u32_e64 v31, vcc, 0, v21, s[26:27]
	global_load_dwordx2 v[62:63], v[36:37], off
	global_load_dwordx2 v[60:61], v[34:35], off
	global_load_dwordx2 v[56:57], v[32:33], off
	global_load_dwordx2 v[50:51], v[30:31], off
	s_waitcnt vmcnt(17)
	v_lshlrev_b32_e32 v84, 16, v86
	ds_read_b128 v[10:13], v100 offset:32256
	ds_read_b128 v[6:9], v100
	v_and_b32_e32 v85, 0xffff0000, v86
	v_lshlrev_b32_e32 v86, 16, v87
	v_and_b32_e32 v87, 0xffff0000, v87
	s_waitcnt lgkmcnt(1)
	v_pk_fma_f32 v[84:85], v[2:3], v[10:11], v[84:85]
	v_pk_fma_f32 v[86:87], v[4:5], v[12:13], v[86:87]
	s_waitcnt lgkmcnt(0)
	v_pk_mul_f32 v[6:7], v[6:7], v[84:85]
	v_pk_mul_f32 v[8:9], v[8:9], v[86:87]
	v_cvt_pk_bf16_f32 v6, v6, v7
	v_cvt_pk_bf16_f32 v7, v8, v9
	global_store_dwordx2 v[80:81], v[6:7], off
	ds_read_b128 v[6:9], v100 offset:32768
	ds_read_b128 v[10:13], v100 offset:33280
	ds_read_b128 v[104:107], v100 offset:7168
	ds_read_b128 v[2:5], v100 offset:512
	s_cmp_lt_u32 s41, 63
	s_waitcnt vmcnt(16)
	v_lshlrev_b32_e32 v80, 16, v82
	v_and_b32_e32 v81, 0xffff0000, v82
	v_lshlrev_b32_e32 v82, 16, v83
	v_and_b32_e32 v83, 0xffff0000, v83
	s_waitcnt lgkmcnt(3)
	v_pk_fma_f32 v[6:7], v[84:85], v[6:7], v[80:81]
	v_pk_fma_f32 v[8:9], v[86:87], v[8:9], v[82:83]
	s_waitcnt lgkmcnt(0)
	v_pk_mul_f32 v[2:3], v[2:3], v[6:7]
	v_pk_mul_f32 v[4:5], v[4:5], v[8:9]
	v_cvt_pk_bf16_f32 v2, v2, v3
	v_cvt_pk_bf16_f32 v3, v4, v5
	global_store_dwordx2 v[58:59], v[2:3], off
	ds_read_b128 v[2:5], v100 offset:1024
	s_waitcnt vmcnt(16)
	v_lshlrev_b32_e32 v58, 16, v78
	v_and_b32_e32 v59, 0xffff0000, v78
	v_lshlrev_b32_e32 v78, 16, v79
	v_and_b32_e32 v79, 0xffff0000, v79
	v_pk_fma_f32 v[58:59], v[10:11], v[6:7], v[58:59]
	v_pk_fma_f32 v[78:79], v[12:13], v[8:9], v[78:79]
	ds_read_b128 v[6:9], v100 offset:1536
	s_waitcnt lgkmcnt(1)
	v_pk_mul_f32 v[4:5], v[4:5], v[78:79]
	v_pk_mul_f32 v[2:3], v[2:3], v[58:59]
	ds_read_b128 v[10:13], v100 offset:34304
	v_cvt_pk_bf16_f32 v2, v2, v3
	v_cvt_pk_bf16_f32 v3, v4, v5
	global_store_dwordx2 v[54:55], v[2:3], off
	ds_read_b128 v[2:5], v100 offset:33792
	s_waitcnt vmcnt(16)
	v_lshlrev_b32_e32 v54, 16, v76
	v_and_b32_e32 v55, 0xffff0000, v76
	v_lshlrev_b32_e32 v76, 16, v77
	v_and_b32_e32 v77, 0xffff0000, v77
	s_waitcnt lgkmcnt(0)
	v_pk_fma_f32 v[54:55], v[58:59], v[2:3], v[54:55]
	v_pk_fma_f32 v[58:59], v[78:79], v[4:5], v[76:77]
	v_pk_mul_f32 v[4:5], v[6:7], v[54:55]
	v_pk_mul_f32 v[2:3], v[8:9], v[58:59]
	v_cvt_pk_bf16_f32 v4, v4, v5
	v_cvt_pk_bf16_f32 v5, v2, v3
	global_store_dwordx2 v[52:53], v[4:5], off
	ds_read_b128 v[2:5], v100 offset:2048
	s_waitcnt vmcnt(13)
	v_lshlrev_b32_e32 v6, 16, v74
	v_and_b32_e32 v7, 0xffff0000, v74
	v_lshlrev_b32_e32 v8, 16, v75
	v_and_b32_e32 v9, 0xffff0000, v75
	v_pk_fma_f32 v[52:53], v[54:55], v[10:11], v[6:7]
	v_pk_fma_f32 v[54:55], v[58:59], v[12:13], v[8:9]
	ds_read_b128 v[6:9], v100 offset:2560
	s_waitcnt lgkmcnt(1)
	v_pk_mul_f32 v[4:5], v[4:5], v[54:55]
	v_pk_mul_f32 v[2:3], v[2:3], v[52:53]
	s_waitcnt vmcnt(12)
; #define LAS __attribute__((address_space(3)))
; __device__ __forceinline__ unsigned cvtpk(float lo, float hi) { f32x2 v = {lo, hi}; bf16x2_t b = __builtin_convertvector(v, bf16x2_t); return __builtin_bit_cast(unsigned, b); }
; __device__ __forceinline__ void gla_scan(const Params& p, LAS unsigned char* lds, int wave) {
;     ...
;             for (int i = 0; i < 16; ++i) { const int cn = 16 * cb + i + 1;
;                 if (cn < 64) {
;                     const f32x4 e3 = *(const LAS f32x4*)(lds + 32768 + ((cn - 1) * 128 + dk) * 4), e1 = *(const LAS f32x4*)(lds + (cn * 128 + dk) * 4);
;                     const f32x4 uf = (f32x4){bflo(ucur.x), bfhi(ucur.x), bflo(ucur.y), bfhi(ucur.y)};
;                     s = e3 * s + uf;
;                     const f32x4 o = e1 * s; u32x2 w; w.x = cvtpk(o[0], o[1]); w.y = cvtpk(o[2], o[3]);
;                     base[(size_t)cn * 8192] = w; ucur = uu[i]; } }
	v_lshlrev_b32_e32 v58, 16, v73
	v_cvt_pk_bf16_f32 v2, v2, v3
	v_cvt_pk_bf16_f32 v3, v4, v5
	global_store_dwordx2 v[48:49], v[2:3], off
	ds_read_b128 v[2:5], v100 offset:34816
	ds_read_b128 v[10:13], v100 offset:35328
	v_lshlrev_b32_e32 v48, 16, v72
	v_and_b32_e32 v49, 0xffff0000, v72
	v_and_b32_e32 v59, 0xffff0000, v73
	s_waitcnt lgkmcnt(1)
	v_pk_fma_f32 v[48:49], v[52:53], v[2:3], v[48:49]
	v_pk_fma_f32 v[52:53], v[54:55], v[4:5], v[58:59]
	v_pk_mul_f32 v[4:5], v[6:7], v[48:49]
	v_pk_mul_f32 v[2:3], v[8:9], v[52:53]
	v_cvt_pk_bf16_f32 v4, v4, v5
	v_cvt_pk_bf16_f32 v5, v2, v3
	global_store_dwordx2 v[46:47], v[4:5], off
	ds_read_b128 v[2:5], v100 offset:3072
	s_waitcnt vmcnt(13)
	v_lshlrev_b32_e32 v6, 16, v70
	v_and_b32_e32 v7, 0xffff0000, v70
	v_lshlrev_b32_e32 v8, 16, v71
	v_and_b32_e32 v9, 0xffff0000, v71
	s_waitcnt lgkmcnt(1)
	v_pk_fma_f32 v[46:47], v[48:49], v[10:11], v[6:7]
	v_pk_fma_f32 v[48:49], v[52:53], v[12:13], v[8:9]
	ds_read_b128 v[6:9], v100 offset:3584
	s_waitcnt lgkmcnt(1)
	v_pk_mul_f32 v[4:5], v[4:5], v[48:49]
	v_pk_mul_f32 v[2:3], v[2:3], v[46:47]
	s_waitcnt vmcnt(12)
	v_lshlrev_b32_e32 v52, 16, v69
	v_cvt_pk_bf16_f32 v2, v2, v3
	v_cvt_pk_bf16_f32 v3, v4, v5
	global_store_dwordx2 v[44:45], v[2:3], off
	ds_read_b128 v[2:5], v100 offset:35840
	ds_read_b128 v[10:13], v100 offset:36352
	v_lshlrev_b32_e32 v44, 16, v68
	v_and_b32_e32 v45, 0xffff0000, v68
	v_and_b32_e32 v53, 0xffff0000, v69
	s_waitcnt lgkmcnt(1)
	v_pk_fma_f32 v[44:45], v[46:47], v[2:3], v[44:45]
	v_pk_fma_f32 v[46:47], v[48:49], v[4:5], v[52:53]
	v_pk_mul_f32 v[4:5], v[6:7], v[44:45]
	v_pk_mul_f32 v[2:3], v[8:9], v[46:47]
	v_cvt_pk_bf16_f32 v4, v4, v5
	v_cvt_pk_bf16_f32 v5, v2, v3
	global_store_dwordx2 v[42:43], v[4:5], off
	ds_read_b128 v[2:5], v100 offset:4096
	s_waitcnt vmcnt(13)
	v_lshlrev_b32_e32 v6, 16, v66
	v_and_b32_e32 v7, 0xffff0000, v66
	v_lshlrev_b32_e32 v8, 16, v67
	v_and_b32_e32 v9, 0xffff0000, v67
	s_waitcnt lgkmcnt(1)
	v_pk_fma_f32 v[42:43], v[44:45], v[10:11], v[6:7]
	v_pk_fma_f32 v[44:45], v[46:47], v[12:13], v[8:9]
	ds_read_b128 v[6:9], v100 offset:4608
	s_waitcnt lgkmcnt(1)
	v_pk_mul_f32 v[4:5], v[4:5], v[44:45]
	v_pk_mul_f32 v[2:3], v[2:3], v[42:43]
	s_waitcnt vmcnt(12)
	v_lshlrev_b32_e32 v46, 16, v65
	v_cvt_pk_bf16_f32 v2, v2, v3
	v_cvt_pk_bf16_f32 v3, v4, v5
	global_store_dwordx2 v[40:41], v[2:3], off
	ds_read_b128 v[2:5], v100 offset:36864
	ds_read_b128 v[10:13], v100 offset:37376
	v_lshlrev_b32_e32 v40, 16, v64
	v_and_b32_e32 v41, 0xffff0000, v64
	v_and_b32_e32 v47, 0xffff0000, v65
	s_waitcnt lgkmcnt(1)
	v_pk_fma_f32 v[40:41], v[42:43], v[2:3], v[40:41]
	v_pk_fma_f32 v[42:43], v[44:45], v[4:5], v[46:47]
	v_pk_mul_f32 v[4:5], v[6:7], v[40:41]
	v_pk_mul_f32 v[2:3], v[8:9], v[42:43]
	v_cvt_pk_bf16_f32 v4, v4, v5
	v_cvt_pk_bf16_f32 v5, v2, v3
	global_store_dwordx2 v[36:37], v[4:5], off
	ds_read_b128 v[2:5], v100 offset:5120
	s_waitcnt vmcnt(13)
	v_lshlrev_b32_e32 v6, 16, v62
	v_and_b32_e32 v7, 0xffff0000, v62
	v_lshlrev_b32_e32 v8, 16, v63
	v_and_b32_e32 v9, 0xffff0000, v63
	s_waitcnt lgkmcnt(1)
	v_pk_fma_f32 v[36:37], v[40:41], v[10:11], v[6:7]
	v_pk_fma_f32 v[40:41], v[42:43], v[12:13], v[8:9]
	ds_read_b128 v[6:9], v100 offset:5632
	s_waitcnt lgkmcnt(1)
	v_pk_mul_f32 v[4:5], v[4:5], v[40:41]
	v_pk_mul_f32 v[2:3], v[2:3], v[36:37]
	s_waitcnt vmcnt(12)
	v_lshlrev_b32_e32 v42, 16, v61
	v_cvt_pk_bf16_f32 v2, v2, v3
	v_cvt_pk_bf16_f32 v3, v4, v5
	global_store_dwordx2 v[34:35], v[2:3], off
	ds_read_b128 v[2:5], v100 offset:37888
	ds_read_b128 v[10:13], v100 offset:38400
	v_lshlrev_b32_e32 v34, 16, v60
	v_and_b32_e32 v35, 0xffff0000, v60
	v_and_b32_e32 v43, 0xffff0000, v61
	s_waitcnt lgkmcnt(1)
	v_pk_fma_f32 v[34:35], v[36:37], v[2:3], v[34:35]
	v_pk_fma_f32 v[36:37], v[40:41], v[4:5], v[42:43]
	v_pk_mul_f32 v[4:5], v[6:7], v[34:35]
	v_pk_mul_f32 v[2:3], v[8:9], v[36:37]
	v_cvt_pk_bf16_f32 v4, v4, v5
	v_cvt_pk_bf16_f32 v5, v2, v3
	global_store_dwordx2 v[32:33], v[4:5], off
	ds_read_b128 v[2:5], v100 offset:6144
	s_waitcnt vmcnt(13)
	v_lshlrev_b32_e32 v6, 16, v56
	v_and_b32_e32 v7, 0xffff0000, v56
	v_lshlrev_b32_e32 v8, 16, v57
	v_and_b32_e32 v9, 0xffff0000, v57
	s_waitcnt lgkmcnt(1)
	v_pk_fma_f32 v[32:33], v[34:35], v[10:11], v[6:7]
	v_pk_fma_f32 v[34:35], v[36:37], v[12:13], v[8:9]
	ds_read_b128 v[6:9], v100 offset:6656
	s_waitcnt lgkmcnt(1)
	v_pk_mul_f32 v[4:5], v[4:5], v[34:35]
	v_pk_mul_f32 v[2:3], v[2:3], v[32:33]
	s_waitcnt vmcnt(12)
	v_lshlrev_b32_e32 v36, 16, v51
	v_cvt_pk_bf16_f32 v2, v2, v3
	v_cvt_pk_bf16_f32 v3, v4, v5
	global_store_dwordx2 v[30:31], v[2:3], off
	ds_read_b128 v[2:5], v100 offset:38912
	ds_read_b128 v[10:13], v100 offset:39424
	v_lshlrev_b32_e32 v30, 16, v50
	v_and_b32_e32 v31, 0xffff0000, v50
	v_and_b32_e32 v37, 0xffff0000, v51
	s_waitcnt lgkmcnt(1)
	v_pk_fma_f32 v[2:3], v[32:33], v[2:3], v[30:31]
	v_pk_fma_f32 v[4:5], v[34:35], v[4:5], v[36:37]
	v_pk_mul_f32 v[6:7], v[6:7], v[2:3]
	v_pk_mul_f32 v[8:9], v[8:9], v[4:5]
	v_cvt_pk_bf16_f32 v6, v6, v7
	v_cvt_pk_bf16_f32 v7, v8, v9
	global_store_dwordx2 v[26:27], v[6:7], off
	v_lshlrev_b32_e32 v6, 16, v38
	v_and_b32_e32 v7, 0xffff0000, v38
	v_lshlrev_b32_e32 v8, 16, v39
	v_and_b32_e32 v9, 0xffff0000, v39
	s_waitcnt lgkmcnt(0)
	v_pk_fma_f32 v[2:3], v[2:3], v[10:11], v[6:7]
	v_pk_fma_f32 v[4:5], v[4:5], v[12:13], v[8:9]
	v_pk_mul_f32 v[8:9], v[104:105], v[2:3]
	v_pk_mul_f32 v[6:7], v[106:107], v[4:5]
	v_cvt_pk_bf16_f32 v8, v8, v9
	v_cvt_pk_bf16_f32 v9, v6, v7
	global_store_dwordx2 v[24:25], v[8:9], off
	s_cbranch_scc1 .LBB0_662
	v_mov_b64_e32 v[22:23], v[28:29]
	s_branch .LBB0_663

;     __device__ __forceinline__ void operator()(const f32x4 (&acc)[2][2][4][2], const Unit& u, int wr, int wc, int fr, int fq) const {
;     ...
;         for (int ai = 0; ai < 2; ++ai)
; #pragma unroll
;             for (int m = 0; m < 4; ++m) { const size_t off = (size_t)(u.pm * BM + ai * HALF + wr * 64 + m * 16 + fr) * ldc + col0;
; #pragma unroll
;                 for (int bj = 0; bj < 2; ++bj)
; #pragma unroll
;                     for (int n = 0; n < 2; ++n) { const u32x2 t = *(const u32x2*)(base + off + bj * HALF + n * 16);
;                         const f32x4 bs = (f32x4){__builtin_bit_cast(float, t.x << 16), __builtin_bit_cast(float, t.x & 0xffff0000u), __builtin_bit_cast(float, t.y << 16), __builtin_bit_cast(float, t.y & 0xffff0000u)};
;                         *(f32x4*)(out + off + bj * HALF + n * 16) = bs + acc[ai][bj][m][n] * scale; } }
.LBB0_1012:
	s_and_b64 vcc, exec, s[0:1]
	s_mov_b64 s[0:1], -1
	v_lshlrev_b32_e32 v142, 1, v143
	s_waitcnt vmcnt(28)
	v_mov_b32_e32 v140, v142
	v_lshlrev_b32_e32 v216, 16, v152
	v_and_b32_e32 v217, 0xffff0000, v152
	v_lshlrev_b32_e32 v218, 16, v153
	v_and_b32_e32 v219, 0xffff0000, v153
	v_pk_fma_f32 v[124:125], v[124:125], 0.5, v[216:217] op_sel_hi:[1,0,1]
	v_pk_fma_f32 v[126:127], v[126:127], 0.5, v[218:219] op_sel_hi:[1,0,1]
	global_store_dwordx4 v140, v[124:127], s[8:9] nt
	v_lshlrev_b32_e32 v216, 16, v154
	v_and_b32_e32 v217, 0xffff0000, v154
	v_lshlrev_b32_e32 v218, 16, v155
	v_and_b32_e32 v219, 0xffff0000, v155
	v_pk_fma_f32 v[120:121], v[120:121], 0.5, v[216:217] op_sel_hi:[1,0,1]
	v_pk_fma_f32 v[122:123], v[122:123], 0.5, v[218:219] op_sel_hi:[1,0,1]
	global_store_dwordx4 v140, v[120:123], s[8:9] offset:64 nt
	v_lshlrev_b32_e32 v216, 16, v156
	v_and_b32_e32 v217, 0xffff0000, v156
	v_lshlrev_b32_e32 v218, 16, v157
	v_and_b32_e32 v219, 0xffff0000, v157
	v_pk_fma_f32 v[116:117], v[116:117], 0.5, v[216:217] op_sel_hi:[1,0,1]
	v_pk_fma_f32 v[118:119], v[118:119], 0.5, v[218:219] op_sel_hi:[1,0,1]
	global_store_dwordx4 v140, v[116:119], s[8:9] offset:512 nt
	v_lshlrev_b32_e32 v216, 16, v158
	v_and_b32_e32 v217, 0xffff0000, v158
	v_lshlrev_b32_e32 v218, 16, v159
	v_and_b32_e32 v219, 0xffff0000, v159
	v_pk_fma_f32 v[108:109], v[108:109], 0.5, v[216:217] op_sel_hi:[1,0,1]
	v_pk_fma_f32 v[110:111], v[110:111], 0.5, v[218:219] op_sel_hi:[1,0,1]
	global_store_dwordx4 v140, v[108:111], s[8:9] offset:576 nt
	s_waitcnt vmcnt(28)
	v_add_u32_e32 v140, 0x20000, v142
	v_lshlrev_b32_e32 v216, 16, v160
	v_and_b32_e32 v217, 0xffff0000, v160
	v_lshlrev_b32_e32 v218, 16, v161
	v_and_b32_e32 v219, 0xffff0000, v161
	v_pk_fma_f32 v[112:113], v[112:113], 0.5, v[216:217] op_sel_hi:[1,0,1]
	v_pk_fma_f32 v[114:115], v[114:115], 0.5, v[218:219] op_sel_hi:[1,0,1]
	global_store_dwordx4 v140, v[112:115], s[8:9] nt
	v_lshlrev_b32_e32 v216, 16, v162
	v_and_b32_e32 v217, 0xffff0000, v162
	v_lshlrev_b32_e32 v218, 16, v163
	v_and_b32_e32 v219, 0xffff0000, v163
	v_pk_fma_f32 v[104:105], v[104:105], 0.5, v[216:217] op_sel_hi:[1,0,1]
	v_pk_fma_f32 v[106:107], v[106:107], 0.5, v[218:219] op_sel_hi:[1,0,1]
	global_store_dwordx4 v140, v[104:107], s[8:9] offset:64 nt
	v_lshlrev_b32_e32 v216, 16, v164
	v_and_b32_e32 v217, 0xffff0000, v164
	v_lshlrev_b32_e32 v218, 16, v165
	v_and_b32_e32 v219, 0xffff0000, v165
	v_pk_fma_f32 v[100:101], v[100:101], 0.5, v[216:217] op_sel_hi:[1,0,1]
	v_pk_fma_f32 v[102:103], v[102:103], 0.5, v[218:219] op_sel_hi:[1,0,1]
	global_store_dwordx4 v140, v[100:103], s[8:9] offset:512 nt
	v_lshlrev_b32_e32 v216, 16, v166
	v_and_b32_e32 v217, 0xffff0000, v166
	v_lshlrev_b32_e32 v218, 16, v167
	v_and_b32_e32 v219, 0xffff0000, v167
	v_pk_fma_f32 v[92:93], v[92:93], 0.5, v[216:217] op_sel_hi:[1,0,1]
	v_pk_fma_f32 v[94:95], v[94:95], 0.5, v[218:219] op_sel_hi:[1,0,1]
	global_store_dwordx4 v140, v[92:95], s[8:9] offset:576 nt
	s_waitcnt vmcnt(28)
	v_add_u32_e32 v140, 0x40000, v142
	v_lshlrev_b32_e32 v216, 16, v168
	v_and_b32_e32 v217, 0xffff0000, v168
	v_lshlrev_b32_e32 v218, 16, v169
	v_and_b32_e32 v219, 0xffff0000, v169
	v_pk_fma_f32 v[96:97], v[96:97], 0.5, v[216:217] op_sel_hi:[1,0,1]
	v_pk_fma_f32 v[98:99], v[98:99], 0.5, v[218:219] op_sel_hi:[1,0,1]
	global_store_dwordx4 v140, v[96:99], s[8:9] nt
	v_lshlrev_b32_e32 v216, 16, v170
	v_and_b32_e32 v217, 0xffff0000, v170
	v_lshlrev_b32_e32 v218, 16, v171
	v_and_b32_e32 v219, 0xffff0000, v171
	v_pk_fma_f32 v[88:89], v[88:89], 0.5, v[216:217] op_sel_hi:[1,0,1]
	v_pk_fma_f32 v[90:91], v[90:91], 0.5, v[218:219] op_sel_hi:[1,0,1]
	global_store_dwordx4 v140, v[88:91], s[8:9] offset:64 nt
	v_lshlrev_b32_e32 v216, 16, v172
	v_and_b32_e32 v217, 0xffff0000, v172
	v_lshlrev_b32_e32 v218, 16, v173
	v_and_b32_e32 v219, 0xffff0000, v173
	v_pk_fma_f32 v[84:85], v[84:85], 0.5, v[216:217] op_sel_hi:[1,0,1]
	v_pk_fma_f32 v[86:87], v[86:87], 0.5, v[218:219] op_sel_hi:[1,0,1]
	global_store_dwordx4 v140, v[84:87], s[8:9] offset:512 nt
	v_lshlrev_b32_e32 v216, 16, v174
	v_and_b32_e32 v217, 0xffff0000, v174
	v_lshlrev_b32_e32 v218, 16, v175
	v_and_b32_e32 v219, 0xffff0000, v175
	v_pk_fma_f32 v[76:77], v[76:77], 0.5, v[216:217] op_sel_hi:[1,0,1]
	v_pk_fma_f32 v[78:79], v[78:79], 0.5, v[218:219] op_sel_hi:[1,0,1]
	global_store_dwordx4 v140, v[76:79], s[8:9] offset:576 nt
	s_waitcnt vmcnt(28)
	v_add_u32_e32 v140, 0x60000, v142
	v_lshlrev_b32_e32 v216, 16, v176
	v_and_b32_e32 v217, 0xffff0000, v176
	v_lshlrev_b32_e32 v218, 16, v177
	v_and_b32_e32 v219, 0xffff0000, v177
	v_pk_fma_f32 v[80:81], v[80:81], 0.5, v[216:217] op_sel_hi:[1,0,1]
	v_pk_fma_f32 v[82:83], v[82:83], 0.5, v[218:219] op_sel_hi:[1,0,1]
	global_store_dwordx4 v140, v[80:83], s[8:9] nt
	v_lshlrev_b32_e32 v216, 16, v178
	v_and_b32_e32 v217, 0xffff0000, v178
	v_lshlrev_b32_e32 v218, 16, v179
	v_and_b32_e32 v219, 0xffff0000, v179
	v_pk_fma_f32 v[72:73], v[72:73], 0.5, v[216:217] op_sel_hi:[1,0,1]
	v_pk_fma_f32 v[74:75], v[74:75], 0.5, v[218:219] op_sel_hi:[1,0,1]
	global_store_dwordx4 v140, v[72:75], s[8:9] offset:64 nt
	v_lshlrev_b32_e32 v216, 16, v180
	v_and_b32_e32 v217, 0xffff0000, v180
	v_lshlrev_b32_e32 v218, 16, v181
	v_and_b32_e32 v219, 0xffff0000, v181
	v_pk_fma_f32 v[68:69], v[68:69], 0.5, v[216:217] op_sel_hi:[1,0,1]
	v_pk_fma_f32 v[70:71], v[70:71], 0.5, v[218:219] op_sel_hi:[1,0,1]
	global_store_dwordx4 v140, v[68:71], s[8:9] offset:512 nt
	v_lshlrev_b32_e32 v216, 16, v182
	v_and_b32_e32 v217, 0xffff0000, v182
	v_lshlrev_b32_e32 v218, 16, v183
	v_and_b32_e32 v219, 0xffff0000, v183
	v_pk_fma_f32 v[64:65], v[64:65], 0.5, v[216:217] op_sel_hi:[1,0,1]
	v_pk_fma_f32 v[66:67], v[66:67], 0.5, v[218:219] op_sel_hi:[1,0,1]
	global_store_dwordx4 v140, v[64:67], s[8:9] offset:576 nt
	s_waitcnt vmcnt(28)
; #define PG8_BAR __builtin_amdgcn_s_barrier()
;     __device__ __forceinline__ void operator()(const f32x4 (&acc)[2][2][4][2], const Unit& u, int wr, int wc, int fr, int fq) const {
;     ...
;             for (int m = 0; m < 4; ++m) { const size_t off = (size_t)(u.pm * BM + ai * HALF + wr * 64 + m * 16 + fr) * ldc + col0;
; #pragma unroll
;                 for (int bj = 0; bj < 2; ++bj)
; #pragma unroll
;                     for (int n = 0; n < 2; ++n) { const u32x2 t = *(const u32x2*)(base + off + bj * HALF + n * 16);
;                         const f32x4 bs = (f32x4){__builtin_bit_cast(float, t.x << 16), __builtin_bit_cast(float, t.x & 0xffff0000u), __builtin_bit_cast(float, t.y << 16), __builtin_bit_cast(float, t.y & 0xffff0000u)};
;                         *(f32x4*)(out + off + bj * HALF + n * 16) = bs + acc[ai][bj][m][n] * scale; } }
; template <class Epi, class Sched, bool ALIGN_EPI = false, bool SP2 = false>
; __device__ __forceinline__ void gemm_phase(PG8_LAS unsigned char* lds, const Gemm g, const Sched& S, const Epi& E, int wave_in) {
;     ...
;         if (!has_next) break;
; #pragma unroll
;         for (int a = 0; a < 2; ++a)
; #pragma unroll
;             for (int b = 0; b < 2; ++b)
; #pragma unroll
;                 for (int m = 0; m < 4; ++m)
; #pragma unroll
;                     for (int n = 0; n < 2; ++n) acc[a][b][m][n] = (f32x4){0.f, 0.f, 0.f, 0.f};
;         cur = nxt; cA = nA; cB = nB; ++ui;
;         if constexpr (ALIGN_EPI) { if (wr == 1) PG8_BAR; }
	v_add_u32_e32 v140, 0x100000, v142
	v_lshlrev_b32_e32 v216, 16, v184
	v_and_b32_e32 v217, 0xffff0000, v184
	v_lshlrev_b32_e32 v218, 16, v185
	v_and_b32_e32 v219, 0xffff0000, v185
	v_pk_fma_f32 v[60:61], v[60:61], 0.5, v[216:217] op_sel_hi:[1,0,1]
	v_pk_fma_f32 v[62:63], v[62:63], 0.5, v[218:219] op_sel_hi:[1,0,1]
	global_store_dwordx4 v140, v[60:63], s[8:9] nt
	v_lshlrev_b32_e32 v216, 16, v186
	v_and_b32_e32 v217, 0xffff0000, v186
	v_lshlrev_b32_e32 v218, 16, v187
	v_and_b32_e32 v219, 0xffff0000, v187
	v_pk_fma_f32 v[56:57], v[56:57], 0.5, v[216:217] op_sel_hi:[1,0,1]
	v_pk_fma_f32 v[58:59], v[58:59], 0.5, v[218:219] op_sel_hi:[1,0,1]
	global_store_dwordx4 v140, v[56:59], s[8:9] offset:64 nt
	v_lshlrev_b32_e32 v216, 16, v188
	v_and_b32_e32 v217, 0xffff0000, v188
	v_lshlrev_b32_e32 v218, 16, v189
	v_and_b32_e32 v219, 0xffff0000, v189
	v_pk_fma_f32 v[52:53], v[52:53], 0.5, v[216:217] op_sel_hi:[1,0,1]
	v_pk_fma_f32 v[54:55], v[54:55], 0.5, v[218:219] op_sel_hi:[1,0,1]
	global_store_dwordx4 v140, v[52:55], s[8:9] offset:512 nt
	v_lshlrev_b32_e32 v216, 16, v190
	v_and_b32_e32 v217, 0xffff0000, v190
	v_lshlrev_b32_e32 v218, 16, v191
	v_and_b32_e32 v219, 0xffff0000, v191
	v_pk_fma_f32 v[44:45], v[44:45], 0.5, v[216:217] op_sel_hi:[1,0,1]
	v_pk_fma_f32 v[46:47], v[46:47], 0.5, v[218:219] op_sel_hi:[1,0,1]
	global_store_dwordx4 v140, v[44:47], s[8:9] offset:576 nt
	s_waitcnt vmcnt(28)
	v_add_u32_e32 v140, 0x120000, v142
	v_lshlrev_b32_e32 v216, 16, v192
	v_and_b32_e32 v217, 0xffff0000, v192
	v_lshlrev_b32_e32 v218, 16, v193
	v_and_b32_e32 v219, 0xffff0000, v193
	v_pk_fma_f32 v[48:49], v[48:49], 0.5, v[216:217] op_sel_hi:[1,0,1]
	v_pk_fma_f32 v[50:51], v[50:51], 0.5, v[218:219] op_sel_hi:[1,0,1]
	global_store_dwordx4 v140, v[48:51], s[8:9] nt
	v_lshlrev_b32_e32 v216, 16, v194
	v_and_b32_e32 v217, 0xffff0000, v194
	v_lshlrev_b32_e32 v218, 16, v195
	v_and_b32_e32 v219, 0xffff0000, v195
	v_pk_fma_f32 v[40:41], v[40:41], 0.5, v[216:217] op_sel_hi:[1,0,1]
	v_pk_fma_f32 v[42:43], v[42:43], 0.5, v[218:219] op_sel_hi:[1,0,1]
	global_store_dwordx4 v140, v[40:43], s[8:9] offset:64 nt
	v_lshlrev_b32_e32 v216, 16, v196
	v_and_b32_e32 v217, 0xffff0000, v196
	v_lshlrev_b32_e32 v218, 16, v197
	v_and_b32_e32 v219, 0xffff0000, v197
	v_pk_fma_f32 v[36:37], v[36:37], 0.5, v[216:217] op_sel_hi:[1,0,1]
	v_pk_fma_f32 v[38:39], v[38:39], 0.5, v[218:219] op_sel_hi:[1,0,1]
	global_store_dwordx4 v140, v[36:39], s[8:9] offset:512 nt
	v_lshlrev_b32_e32 v216, 16, v198
	v_and_b32_e32 v217, 0xffff0000, v198
	v_lshlrev_b32_e32 v218, 16, v199
	v_and_b32_e32 v219, 0xffff0000, v199
	v_pk_fma_f32 v[28:29], v[28:29], 0.5, v[216:217] op_sel_hi:[1,0,1]
	v_pk_fma_f32 v[30:31], v[30:31], 0.5, v[218:219] op_sel_hi:[1,0,1]
	global_store_dwordx4 v140, v[28:31], s[8:9] offset:576 nt
	s_waitcnt vmcnt(28)
	v_add_u32_e32 v140, 0x140000, v142
	v_lshlrev_b32_e32 v216, 16, v200
	v_and_b32_e32 v217, 0xffff0000, v200
	v_lshlrev_b32_e32 v218, 16, v201
	v_and_b32_e32 v219, 0xffff0000, v201
	v_pk_fma_f32 v[32:33], v[32:33], 0.5, v[216:217] op_sel_hi:[1,0,1]
	v_pk_fma_f32 v[34:35], v[34:35], 0.5, v[218:219] op_sel_hi:[1,0,1]
	global_store_dwordx4 v140, v[32:35], s[8:9] nt
	v_lshlrev_b32_e32 v216, 16, v202
	v_and_b32_e32 v217, 0xffff0000, v202
	v_lshlrev_b32_e32 v218, 16, v203
	v_and_b32_e32 v219, 0xffff0000, v203
	v_pk_fma_f32 v[24:25], v[24:25], 0.5, v[216:217] op_sel_hi:[1,0,1]
	v_pk_fma_f32 v[26:27], v[26:27], 0.5, v[218:219] op_sel_hi:[1,0,1]
	global_store_dwordx4 v140, v[24:27], s[8:9] offset:64 nt
	v_lshlrev_b32_e32 v216, 16, v204
	v_and_b32_e32 v217, 0xffff0000, v204
	v_lshlrev_b32_e32 v218, 16, v205
	v_and_b32_e32 v219, 0xffff0000, v205
	v_pk_fma_f32 v[20:21], v[20:21], 0.5, v[216:217] op_sel_hi:[1,0,1]
	v_pk_fma_f32 v[22:23], v[22:23], 0.5, v[218:219] op_sel_hi:[1,0,1]
	global_store_dwordx4 v140, v[20:23], s[8:9] offset:512 nt
	v_lshlrev_b32_e32 v216, 16, v206
	v_and_b32_e32 v217, 0xffff0000, v206
	v_lshlrev_b32_e32 v218, 16, v207
	v_and_b32_e32 v219, 0xffff0000, v207
	v_pk_fma_f32 v[12:13], v[12:13], 0.5, v[216:217] op_sel_hi:[1,0,1]
	v_pk_fma_f32 v[14:15], v[14:15], 0.5, v[218:219] op_sel_hi:[1,0,1]
	global_store_dwordx4 v140, v[12:15], s[8:9] offset:576 nt
	s_waitcnt vmcnt(28)
	v_add_u32_e32 v140, 0x160000, v142
	v_lshlrev_b32_e32 v216, 16, v208
	v_and_b32_e32 v217, 0xffff0000, v208
	v_lshlrev_b32_e32 v218, 16, v209
	v_and_b32_e32 v219, 0xffff0000, v209
	v_pk_fma_f32 v[16:17], v[16:17], 0.5, v[216:217] op_sel_hi:[1,0,1]
	v_pk_fma_f32 v[18:19], v[18:19], 0.5, v[218:219] op_sel_hi:[1,0,1]
	global_store_dwordx4 v140, v[16:19], s[8:9] nt
	v_lshlrev_b32_e32 v216, 16, v210
	v_and_b32_e32 v217, 0xffff0000, v210
	v_lshlrev_b32_e32 v218, 16, v211
	v_and_b32_e32 v219, 0xffff0000, v211
	v_pk_fma_f32 v[8:9], v[8:9], 0.5, v[216:217] op_sel_hi:[1,0,1]
	v_pk_fma_f32 v[10:11], v[10:11], 0.5, v[218:219] op_sel_hi:[1,0,1]
	global_store_dwordx4 v140, v[8:11], s[8:9] offset:64 nt
	v_lshlrev_b32_e32 v216, 16, v212
	v_and_b32_e32 v217, 0xffff0000, v212
	v_lshlrev_b32_e32 v218, 16, v213
	v_and_b32_e32 v219, 0xffff0000, v213
	v_pk_fma_f32 v[4:5], v[4:5], 0.5, v[216:217] op_sel_hi:[1,0,1]
	v_pk_fma_f32 v[6:7], v[6:7], 0.5, v[218:219] op_sel_hi:[1,0,1]
	global_store_dwordx4 v140, v[4:7], s[8:9] offset:512 nt
	v_lshlrev_b32_e32 v216, 16, v214
	v_and_b32_e32 v217, 0xffff0000, v214
	v_lshlrev_b32_e32 v218, 16, v215
	v_and_b32_e32 v219, 0xffff0000, v215
	v_pk_fma_f32 v[0:1], v[0:1], 0.5, v[216:217] op_sel_hi:[1,0,1]
	v_pk_fma_f32 v[2:3], v[2:3], 0.5, v[218:219] op_sel_hi:[1,0,1]
	global_store_dwordx4 v140, v[0:3], s[8:9] offset:576 nt
	s_cbranch_vccnz .LBB0_997
	s_andn2_b64 vcc, exec, s[2:3]
	s_cbranch_vccnz .LBB0_996
	s_barrier
	s_branch .LBB0_996
